# GEMM2 epilogue: second half-tile's gate loads prefetched with the first batch, second half starts from moves (no store drain)
# baseline (speedup 1.0000x reference)
.LBB0_887:
	v_mov_b64_e32 v[160:161], s[94:95]
	v_lshlrev_b32_e32 v2, 1, v214
	v_mad_i64_i32 v[132:133], s[2:3], v212, s20, v[160:161]
	v_mov_b32_e32 v3, v0
	v_lshl_add_u64 v[132:133], v[132:133], 0, v[2:3]
	s_mov_b64 s[6:7], 0x5800
	v_lshl_add_u64 v[134:135], v[132:133], 0, s[6:7]
	v_add_co_u32_e32 v132, vcc, 0x5000, v132
	v_lshl_or_b32 v1, v212, 12, v2
	s_nop 0
	v_addc_co_u32_e32 v133, vcc, 0, v133, vcc
	global_load_dwordx4 v[166:169], v[132:133], off offset:2048
	global_load_dwordx4 v[156:159], v[134:135], off offset:256
	v_mad_i64_i32 v[132:133], s[2:3], v148, s20, v[160:161]
	v_lshl_add_u64 v[132:133], v[132:133], 0, v[2:3]
	v_lshl_add_u64 v[134:135], v[132:133], 0, s[6:7]
	v_add_co_u32_e32 v132, vcc, 0x5000, v132
	s_movk_i32 s4, 0x5000
	s_nop 0
	v_addc_co_u32_e32 v133, vcc, 0, v133, vcc
	global_load_dwordx4 v[152:155], v[132:133], off offset:2048
	global_load_dwordx4 v[148:151], v[134:135], off offset:256
	v_mad_i64_i32 v[132:133], s[2:3], v164, s20, v[160:161]
	v_lshl_add_u64 v[132:133], v[132:133], 0, v[2:3]
	v_lshl_add_u64 v[134:135], v[132:133], 0, s[6:7]
	v_add_co_u32_e32 v132, vcc, 0x5000, v132
	v_add_u32_e32 v213, 0x80, v212
	v_mad_i64_i32 v[218:219], s[2:3], v213, s20, v[160:161]
	v_lshl_add_u64 v[218:219], v[218:219], 0, v[2:3]
	v_lshl_add_u64 v[218:219], v[218:219], 0, s[6:7]
	global_load_dwordx4 v[176:179], v[218:219], off
	global_load_dwordx4 v[180:183], v[218:219], off offset:256
	v_add_u32_e32 v213, 0x90, v212
	v_mad_i64_i32 v[218:219], s[2:3], v213, s20, v[160:161]
	v_lshl_add_u64 v[218:219], v[218:219], 0, v[2:3]
	v_lshl_add_u64 v[218:219], v[218:219], 0, s[6:7]
	global_load_dwordx4 v[184:187], v[218:219], off
	global_load_dwordx4 v[188:191], v[218:219], off offset:256
	v_add_u32_e32 v213, 0xa0, v212
	v_mad_i64_i32 v[218:219], s[2:3], v213, s20, v[160:161]
	v_lshl_add_u64 v[218:219], v[218:219], 0, v[2:3]
	v_lshl_add_u64 v[218:219], v[218:219], 0, s[6:7]
	global_load_dwordx4 v[192:195], v[218:219], off
	global_load_dwordx4 v[244:247], v[218:219], off offset:256
	v_add_u32_e32 v213, 0xb0, v212
	v_mad_i64_i32 v[218:219], s[2:3], v213, s20, v[160:161]
	v_lshl_add_u64 v[218:219], v[218:219], 0, v[2:3]
	v_lshl_add_u64 v[218:219], v[218:219], 0, s[6:7]
	global_load_dwordx4 v[248:251], v[218:219], off
	s_waitcnt vmcnt(7)
	v_lshlrev_b32_e32 v165, 16, v166
	v_mul_f32_e32 v165, 0xbfb8aa3b, v165
	v_exp_f32_e32 v165, v165
	v_addc_co_u32_e32 v133, vcc, 0, v133, vcc
	v_lshlrev_b32_e32 v171, 16, v168
	v_add_f32_e32 v165, 1.0, v165
	v_and_b32_e32 v164, 0xffff0000, v168
	v_div_scale_f32 v168, s[2:3], v165, v165, 1.0
	global_load_dwordx4 v[144:147], v[132:133], off offset:2048
	global_load_dwordx4 v[140:143], v[134:135], off offset:256
	v_mad_i64_i32 v[132:133], s[2:3], v162, s20, v[160:161]
	v_lshlrev_b32_e32 v163, 16, v169
	v_and_b32_e32 v162, 0xffff0000, v169
	v_rcp_f32_e32 v169, v168
	v_lshl_add_u64 v[132:133], v[132:133], 0, v[2:3]
	v_lshl_add_u64 v[134:135], v[132:133], 0, s[6:7]
	v_add_co_u32_e32 v132, vcc, 0x5000, v132
	v_fma_f32 v172, -v168, v169, 1.0
	s_nop 0
	v_addc_co_u32_e32 v133, vcc, 0, v133, vcc
	v_fmac_f32_e32 v169, v172, v169
	v_div_scale_f32 v172, vcc, 1.0, v165, 1.0
	v_mul_f32_e32 v173, v172, v169
	v_fma_f32 v174, -v168, v173, v172
	v_fmac_f32_e32 v173, v174, v169
	v_fma_f32 v168, -v168, v173, v172
	v_div_fmas_f32 v168, v168, v169, v173
	v_and_b32_e32 v166, 0xffff0000, v166
	v_div_fixup_f32 v165, v168, v165, 1.0
	v_mul_f32_e32 v128, v128, v165
	v_mul_f32_e32 v165, 0xbfb8aa3b, v166
	v_exp_f32_e32 v165, v165
	v_lshlrev_b32_e32 v170, 16, v167
	v_and_b32_e32 v167, 0xffff0000, v167
	global_load_dwordx4 v[136:139], v[132:133], off offset:2048
	s_nop 0
	global_load_dwordx4 v[132:135], v[134:135], off offset:256
	v_add_f32_e32 v165, 1.0, v165
	v_div_scale_f32 v166, s[2:3], v165, v165, 1.0
	v_rcp_f32_e32 v168, v166
	s_nop 0
	v_fma_f32 v169, -v166, v168, 1.0
	v_fmac_f32_e32 v168, v169, v168
	v_div_scale_f32 v169, vcc, 1.0, v165, 1.0
	v_mul_f32_e32 v172, v169, v168
	v_fma_f32 v173, -v166, v172, v169
	v_fmac_f32_e32 v172, v173, v168
	v_fma_f32 v166, -v166, v172, v169
	v_div_fmas_f32 v166, v166, v168, v172
	v_div_fixup_f32 v165, v166, v165, 1.0
	v_mul_f32_e32 v129, v129, v165
	v_mul_f32_e32 v165, 0xbfb8aa3b, v170
	v_exp_f32_e32 v165, v165
	s_nop 0
	v_add_f32_e32 v165, 1.0, v165
	v_div_scale_f32 v166, s[2:3], v165, v165, 1.0
	v_rcp_f32_e32 v168, v166
	s_nop 0
	v_fma_f32 v169, -v166, v168, 1.0
	v_fmac_f32_e32 v168, v169, v168
	v_div_scale_f32 v169, vcc, 1.0, v165, 1.0
	v_mul_f32_e32 v170, v169, v168
	v_fma_f32 v172, -v166, v170, v169
	v_fmac_f32_e32 v170, v172, v168
	v_fma_f32 v166, -v166, v170, v169
	v_div_fmas_f32 v166, v166, v168, v170
	v_div_fixup_f32 v165, v166, v165, 1.0
	v_mul_f32_e32 v130, v130, v165
	v_mul_f32_e32 v165, 0xbfb8aa3b, v167
	v_exp_f32_e32 v165, v165
	s_nop 0
	v_add_f32_e32 v165, 1.0, v165
	v_div_scale_f32 v166, s[2:3], v165, v165, 1.0
	v_rcp_f32_e32 v167, v166
	s_nop 0
	v_fma_f32 v168, -v166, v167, 1.0
	v_fmac_f32_e32 v167, v168, v167
	v_div_scale_f32 v168, vcc, 1.0, v165, 1.0
	v_mul_f32_e32 v169, v168, v167
	v_fma_f32 v170, -v166, v169, v168
	v_fmac_f32_e32 v169, v170, v167
	v_fma_f32 v166, -v166, v169, v168
	v_div_fmas_f32 v166, v166, v167, v169
	v_div_fixup_f32 v165, v166, v165, 1.0
	v_mul_f32_e32 v131, v131, v165
	v_mul_f32_e32 v165, 0xbfb8aa3b, v171
	v_exp_f32_e32 v165, v165
	s_nop 0
	v_add_f32_e32 v165, 1.0, v165
	v_div_scale_f32 v166, s[2:3], v165, v165, 1.0
	v_rcp_f32_e32 v167, v166
	s_nop 0
	v_fma_f32 v168, -v166, v167, 1.0
	v_fmac_f32_e32 v167, v168, v167
	v_div_scale_f32 v168, vcc, 1.0, v165, 1.0
	v_mul_f32_e32 v169, v168, v167
	v_fma_f32 v170, -v166, v169, v168
	v_fmac_f32_e32 v169, v170, v167
	v_fma_f32 v166, -v166, v169, v168
	v_div_fmas_f32 v166, v166, v167, v169
	v_div_fixup_f32 v165, v166, v165, 1.0
	v_mul_f32_e32 v165, v124, v165
	v_mul_f32_e32 v124, 0xbfb8aa3b, v164
	v_exp_f32_e32 v124, v124
	s_nop 0
	v_add_f32_e32 v124, 1.0, v124
	v_div_scale_f32 v164, s[2:3], v124, v124, 1.0
	v_rcp_f32_e32 v166, v164
	s_nop 0
	v_fma_f32 v167, -v164, v166, 1.0
	v_fmac_f32_e32 v166, v167, v166
	v_div_scale_f32 v167, vcc, 1.0, v124, 1.0
	v_mul_f32_e32 v168, v167, v166
	v_fma_f32 v169, -v164, v168, v167
	v_fmac_f32_e32 v168, v169, v166
	v_fma_f32 v164, -v164, v168, v167
	v_div_fmas_f32 v164, v164, v166, v168
	v_div_fixup_f32 v124, v164, v124, 1.0
	v_mul_f32_e32 v164, v125, v124
	v_mul_f32_e32 v124, 0xbfb8aa3b, v163
	v_exp_f32_e32 v124, v124
	s_nop 0
	v_add_f32_e32 v124, 1.0, v124
	v_div_scale_f32 v125, s[2:3], v124, v124, 1.0
	v_rcp_f32_e32 v163, v125
	s_nop 0
	v_fma_f32 v166, -v125, v163, 1.0
	v_fmac_f32_e32 v163, v166, v163
	v_div_scale_f32 v166, vcc, 1.0, v124, 1.0
	v_mul_f32_e32 v167, v166, v163
	v_fma_f32 v168, -v125, v167, v166
	v_fmac_f32_e32 v167, v168, v163
	v_fma_f32 v125, -v125, v167, v166
	v_div_fmas_f32 v125, v125, v163, v167
	v_div_fixup_f32 v124, v125, v124, 1.0
	v_mul_f32_e32 v163, v126, v124
	v_mul_f32_e32 v124, 0xbfb8aa3b, v162
	v_exp_f32_e32 v124, v124
	s_nop 0
	v_add_f32_e32 v124, 1.0, v124
	v_div_scale_f32 v125, s[2:3], v124, v124, 1.0
	v_rcp_f32_e32 v126, v125
	s_nop 0
	v_fma_f32 v162, -v125, v126, 1.0
	v_fmac_f32_e32 v126, v162, v126
	v_div_scale_f32 v162, vcc, 1.0, v124, 1.0
	v_mul_f32_e32 v166, v162, v126
	v_fma_f32 v167, -v125, v166, v162
	v_fmac_f32_e32 v166, v167, v126
	v_fma_f32 v125, -v125, v166, v162
	v_div_fmas_f32 v125, v125, v126, v166
	v_div_fixup_f32 v124, v125, v124, 1.0
	v_mul_f32_e32 v127, v127, v124
	v_cvt_pk_bf16_f32 v124, v128, v129
	v_cvt_pk_bf16_f32 v125, v130, v131
	v_cvt_pk_bf16_f32 v126, v165, v164
	v_cvt_pk_bf16_f32 v127, v163, v127
	buffer_store_dwordx4 v[124:127], v1, s[80:83], 0 offen sc1
	v_and_b32_e32 v128, 0xffff0000, v157
	v_lshlrev_b32_e32 v129, 16, v158
	v_lshlrev_b32_e32 v125, 16, v156
	v_mul_f32_e32 v125, 0xbfb8aa3b, v125
	v_exp_f32_e32 v125, v125
	v_and_b32_e32 v126, 0xffff0000, v156
	v_lshlrev_b32_e32 v127, 16, v157
	v_and_b32_e32 v130, 0xffff0000, v158
	v_add_f32_e32 v125, 1.0, v125
	v_div_scale_f32 v156, s[2:3], v125, v125, 1.0
	v_rcp_f32_e32 v157, v156
	v_lshlrev_b32_e32 v131, 16, v159
	v_and_b32_e32 v124, 0xffff0000, v159
	v_fma_f32 v158, -v156, v157, 1.0
	v_fmac_f32_e32 v157, v158, v157
	v_div_scale_f32 v158, vcc, 1.0, v125, 1.0
	v_mul_f32_e32 v159, v158, v157
	v_fma_f32 v162, -v156, v159, v158
	v_fmac_f32_e32 v159, v162, v157
	v_fma_f32 v156, -v156, v159, v158
	v_div_fmas_f32 v156, v156, v157, v159
	v_div_fixup_f32 v125, v156, v125, 1.0
	v_mul_f32_e32 v120, v120, v125
	v_mul_f32_e32 v125, 0xbfb8aa3b, v126
	v_exp_f32_e32 v125, v125
	s_nop 0
	v_add_f32_e32 v125, 1.0, v125
	v_div_scale_f32 v126, s[2:3], v125, v125, 1.0
	v_rcp_f32_e32 v156, v126
	s_nop 0
	v_fma_f32 v157, -v126, v156, 1.0
	v_fmac_f32_e32 v156, v157, v156
	v_div_scale_f32 v157, vcc, 1.0, v125, 1.0
	v_mul_f32_e32 v158, v157, v156
	v_fma_f32 v159, -v126, v158, v157
	v_fmac_f32_e32 v158, v159, v156
	v_fma_f32 v126, -v126, v158, v157
	v_div_fmas_f32 v126, v126, v156, v158
	v_div_fixup_f32 v125, v126, v125, 1.0
	v_mul_f32_e32 v121, v121, v125
	v_mul_f32_e32 v125, 0xbfb8aa3b, v127
	v_exp_f32_e32 v125, v125
	s_nop 0
	v_add_f32_e32 v125, 1.0, v125
	v_div_scale_f32 v126, s[2:3], v125, v125, 1.0
	v_rcp_f32_e32 v127, v126
	s_nop 0
	v_fma_f32 v156, -v126, v127, 1.0
	v_fmac_f32_e32 v127, v156, v127
	v_div_scale_f32 v156, vcc, 1.0, v125, 1.0
	v_mul_f32_e32 v157, v156, v127
	v_fma_f32 v158, -v126, v157, v156
	v_fmac_f32_e32 v157, v158, v127
	v_fma_f32 v126, -v126, v157, v156
	v_div_fmas_f32 v126, v126, v127, v157
	v_div_fixup_f32 v125, v126, v125, 1.0
	v_mul_f32_e32 v122, v122, v125
	v_mul_f32_e32 v125, 0xbfb8aa3b, v128
	v_exp_f32_e32 v125, v125
	s_nop 0
	v_add_f32_e32 v125, 1.0, v125
	v_div_scale_f32 v126, s[2:3], v125, v125, 1.0
	v_rcp_f32_e32 v127, v126
	s_nop 0
	v_fma_f32 v128, -v126, v127, 1.0
	v_fmac_f32_e32 v127, v128, v127
	v_div_scale_f32 v128, vcc, 1.0, v125, 1.0
	v_mul_f32_e32 v156, v128, v127
	v_fma_f32 v157, -v126, v156, v128
	v_fmac_f32_e32 v156, v157, v127
	v_fma_f32 v126, -v126, v156, v128
	v_div_fmas_f32 v126, v126, v127, v156
	v_div_fixup_f32 v125, v126, v125, 1.0
	v_mul_f32_e32 v123, v123, v125
	v_mul_f32_e32 v125, 0xbfb8aa3b, v129
	v_exp_f32_e32 v125, v125
	s_nop 0
	v_add_f32_e32 v125, 1.0, v125
	v_div_scale_f32 v126, s[2:3], v125, v125, 1.0
	v_rcp_f32_e32 v127, v126
	s_nop 0
	v_fma_f32 v128, -v126, v127, 1.0
	v_fmac_f32_e32 v127, v128, v127
	v_div_scale_f32 v128, vcc, 1.0, v125, 1.0
	v_mul_f32_e32 v129, v128, v127
	v_fma_f32 v156, -v126, v129, v128
	v_fmac_f32_e32 v129, v156, v127
	v_fma_f32 v126, -v126, v129, v128
	v_div_fmas_f32 v126, v126, v127, v129
	v_div_fixup_f32 v125, v126, v125, 1.0
	v_mul_f32_e32 v125, v116, v125
	v_mul_f32_e32 v116, 0xbfb8aa3b, v130
	v_exp_f32_e32 v116, v116
	s_nop 0
	v_add_f32_e32 v116, 1.0, v116
	v_div_scale_f32 v126, s[2:3], v116, v116, 1.0
	v_rcp_f32_e32 v127, v126
	s_nop 0
	v_fma_f32 v128, -v126, v127, 1.0
	v_fmac_f32_e32 v127, v128, v127
	v_div_scale_f32 v128, vcc, 1.0, v116, 1.0
	v_mul_f32_e32 v129, v128, v127
	v_fma_f32 v130, -v126, v129, v128
	v_fmac_f32_e32 v129, v130, v127
	v_fma_f32 v126, -v126, v129, v128
	v_div_fmas_f32 v126, v126, v127, v129
	v_div_fixup_f32 v116, v126, v116, 1.0
	v_mul_f32_e32 v126, v117, v116
	v_mul_f32_e32 v116, 0xbfb8aa3b, v131
	v_exp_f32_e32 v116, v116
	s_nop 0
	v_add_f32_e32 v116, 1.0, v116
	v_div_scale_f32 v117, s[2:3], v116, v116, 1.0
	v_rcp_f32_e32 v127, v117
	s_nop 0
	v_fma_f32 v128, -v117, v127, 1.0
	v_fmac_f32_e32 v127, v128, v127
	v_div_scale_f32 v128, vcc, 1.0, v116, 1.0
	v_mul_f32_e32 v129, v128, v127
	v_fma_f32 v130, -v117, v129, v128
	v_fmac_f32_e32 v129, v130, v127
	v_fma_f32 v117, -v117, v129, v128
	v_div_fmas_f32 v117, v117, v127, v129
	v_div_fixup_f32 v116, v117, v116, 1.0
	v_mul_f32_e32 v127, v118, v116
	v_mul_f32_e32 v116, 0xbfb8aa3b, v124
	v_exp_f32_e32 v116, v116
	s_nop 0
	v_add_f32_e32 v116, 1.0, v116
	v_div_scale_f32 v117, s[2:3], v116, v116, 1.0
	v_rcp_f32_e32 v118, v117
	s_nop 0
	v_fma_f32 v124, -v117, v118, 1.0
	v_fmac_f32_e32 v118, v124, v118
	v_div_scale_f32 v124, vcc, 1.0, v116, 1.0
	v_mul_f32_e32 v128, v124, v118
	v_fma_f32 v129, -v117, v128, v124
	v_fmac_f32_e32 v128, v129, v118
	v_fma_f32 v117, -v117, v128, v124
	v_div_fmas_f32 v117, v117, v118, v128
	v_div_fixup_f32 v116, v117, v116, 1.0
	v_mul_f32_e32 v119, v119, v116
	v_cvt_pk_bf16_f32 v116, v120, v121
	v_cvt_pk_bf16_f32 v117, v122, v123
	v_cvt_pk_bf16_f32 v118, v125, v126
	v_cvt_pk_bf16_f32 v119, v127, v119
	buffer_store_dwordx4 v[116:119], v1, s[80:83], 0 offen offset:256 sc1
	v_lshlrev_b32_e32 v120, 16, v153
	v_and_b32_e32 v121, 0xffff0000, v153
	v_lshlrev_b32_e32 v118, 16, v152
	v_mul_f32_e32 v118, 0xbfb8aa3b, v118
	v_exp_f32_e32 v118, v118
	v_and_b32_e32 v119, 0xffff0000, v152
	v_lshlrev_b32_e32 v122, 16, v154
	v_and_b32_e32 v123, 0xffff0000, v154
	v_add_f32_e32 v118, 1.0, v118
	v_div_scale_f32 v125, s[2:3], v118, v118, 1.0
	v_rcp_f32_e32 v126, v125
	v_lshlrev_b32_e32 v124, 16, v155
	v_and_b32_e32 v117, 0xffff0000, v155
	v_add_u32_e32 v116, 0x10000, v1
	v_fma_f32 v127, -v125, v126, 1.0
	v_fmac_f32_e32 v126, v127, v126
	v_div_scale_f32 v127, vcc, 1.0, v118, 1.0
	v_mul_f32_e32 v128, v127, v126
	v_fma_f32 v129, -v125, v128, v127
	v_fmac_f32_e32 v128, v129, v126
	v_fma_f32 v125, -v125, v128, v127
	v_div_fmas_f32 v125, v125, v126, v128
	v_div_fixup_f32 v118, v125, v118, 1.0
	v_mul_f32_e32 v112, v112, v118
	v_mul_f32_e32 v118, 0xbfb8aa3b, v119
	v_exp_f32_e32 v118, v118
	s_nop 0
	v_add_f32_e32 v118, 1.0, v118
	v_div_scale_f32 v119, s[2:3], v118, v118, 1.0
	v_rcp_f32_e32 v125, v119
	s_nop 0
	v_fma_f32 v126, -v119, v125, 1.0
	v_fmac_f32_e32 v125, v126, v125
	v_div_scale_f32 v126, vcc, 1.0, v118, 1.0
	v_mul_f32_e32 v127, v126, v125
	v_fma_f32 v128, -v119, v127, v126
	v_fmac_f32_e32 v127, v128, v125
	v_fma_f32 v119, -v119, v127, v126
	v_div_fmas_f32 v119, v119, v125, v127
	v_div_fixup_f32 v118, v119, v118, 1.0
	v_mul_f32_e32 v113, v113, v118
	v_mul_f32_e32 v118, 0xbfb8aa3b, v120
	v_exp_f32_e32 v118, v118
	s_nop 0
	v_add_f32_e32 v118, 1.0, v118
	v_div_scale_f32 v119, s[2:3], v118, v118, 1.0
	v_rcp_f32_e32 v120, v119
	s_nop 0
	v_fma_f32 v125, -v119, v120, 1.0
	v_fmac_f32_e32 v120, v125, v120
	v_div_scale_f32 v125, vcc, 1.0, v118, 1.0
	v_mul_f32_e32 v126, v125, v120
	v_fma_f32 v127, -v119, v126, v125
	v_fmac_f32_e32 v126, v127, v120
	v_fma_f32 v119, -v119, v126, v125
	v_div_fmas_f32 v119, v119, v120, v126
	v_div_fixup_f32 v118, v119, v118, 1.0
	v_mul_f32_e32 v114, v114, v118
	v_mul_f32_e32 v118, 0xbfb8aa3b, v121
	v_exp_f32_e32 v118, v118
	s_nop 0
	v_add_f32_e32 v118, 1.0, v118
	v_div_scale_f32 v119, s[2:3], v118, v118, 1.0
	v_rcp_f32_e32 v120, v119
	s_nop 0
	v_fma_f32 v121, -v119, v120, 1.0
	v_fmac_f32_e32 v120, v121, v120
	v_div_scale_f32 v121, vcc, 1.0, v118, 1.0
	v_mul_f32_e32 v125, v121, v120
	v_fma_f32 v126, -v119, v125, v121
	v_fmac_f32_e32 v125, v126, v120
	v_fma_f32 v119, -v119, v125, v121
	v_div_fmas_f32 v119, v119, v120, v125
	v_div_fixup_f32 v118, v119, v118, 1.0
	v_mul_f32_e32 v115, v115, v118
	v_mul_f32_e32 v118, 0xbfb8aa3b, v122
	v_exp_f32_e32 v118, v118
	s_nop 0
	v_add_f32_e32 v118, 1.0, v118
	v_div_scale_f32 v119, s[2:3], v118, v118, 1.0
	v_rcp_f32_e32 v120, v119
	s_nop 0
	v_fma_f32 v121, -v119, v120, 1.0
	v_fmac_f32_e32 v120, v121, v120
	v_div_scale_f32 v121, vcc, 1.0, v118, 1.0
	v_mul_f32_e32 v122, v121, v120
	v_fma_f32 v125, -v119, v122, v121
	v_fmac_f32_e32 v122, v125, v120
	v_fma_f32 v119, -v119, v122, v121
	v_div_fmas_f32 v119, v119, v120, v122
	v_div_fixup_f32 v118, v119, v118, 1.0
	v_mul_f32_e32 v118, v108, v118
	v_mul_f32_e32 v108, 0xbfb8aa3b, v123
	v_exp_f32_e32 v108, v108
	s_nop 0
	v_add_f32_e32 v108, 1.0, v108
	v_div_scale_f32 v119, s[2:3], v108, v108, 1.0
	v_rcp_f32_e32 v120, v119
	s_nop 0
	v_fma_f32 v121, -v119, v120, 1.0
	v_fmac_f32_e32 v120, v121, v120
	v_div_scale_f32 v121, vcc, 1.0, v108, 1.0
	v_mul_f32_e32 v122, v121, v120
	v_fma_f32 v123, -v119, v122, v121
	v_fmac_f32_e32 v122, v123, v120
	v_fma_f32 v119, -v119, v122, v121
	v_div_fmas_f32 v119, v119, v120, v122
	v_div_fixup_f32 v108, v119, v108, 1.0
	v_mul_f32_e32 v119, v109, v108
	v_mul_f32_e32 v108, 0xbfb8aa3b, v124
	v_exp_f32_e32 v108, v108
	s_nop 0
	v_add_f32_e32 v108, 1.0, v108
	v_div_scale_f32 v109, s[2:3], v108, v108, 1.0
	v_rcp_f32_e32 v120, v109
	s_nop 0
	v_fma_f32 v121, -v109, v120, 1.0
	v_fmac_f32_e32 v120, v121, v120
	v_div_scale_f32 v121, vcc, 1.0, v108, 1.0
	v_mul_f32_e32 v122, v121, v120
	v_fma_f32 v123, -v109, v122, v121
	v_fmac_f32_e32 v122, v123, v120
	v_fma_f32 v109, -v109, v122, v121
	v_div_fmas_f32 v109, v109, v120, v122
	v_div_fixup_f32 v108, v109, v108, 1.0
	v_mul_f32_e32 v120, v110, v108
	v_mul_f32_e32 v108, 0xbfb8aa3b, v117
	v_exp_f32_e32 v108, v108
	s_nop 0
	v_add_f32_e32 v108, 1.0, v108
	v_div_scale_f32 v109, s[2:3], v108, v108, 1.0
	v_rcp_f32_e32 v110, v109
	s_nop 0
	v_fma_f32 v117, -v109, v110, 1.0
	v_fmac_f32_e32 v110, v117, v110
	v_div_scale_f32 v117, vcc, 1.0, v108, 1.0
	v_mul_f32_e32 v121, v117, v110
	v_fma_f32 v122, -v109, v121, v117
	v_fmac_f32_e32 v121, v122, v110
	v_fma_f32 v109, -v109, v121, v117
	v_div_fmas_f32 v109, v109, v110, v121
	v_div_fixup_f32 v108, v109, v108, 1.0
	v_mul_f32_e32 v111, v111, v108
	v_cvt_pk_bf16_f32 v108, v112, v113
	v_cvt_pk_bf16_f32 v109, v114, v115
	v_cvt_pk_bf16_f32 v110, v118, v119
	v_cvt_pk_bf16_f32 v111, v120, v111
	buffer_store_dwordx4 v[108:111], v116, s[80:83], 0 offen sc1
	v_and_b32_e32 v112, 0xffff0000, v149
	v_lshlrev_b32_e32 v113, 16, v150
	v_lshlrev_b32_e32 v109, 16, v148
	v_mul_f32_e32 v109, 0xbfb8aa3b, v109
	v_exp_f32_e32 v109, v109
	v_and_b32_e32 v110, 0xffff0000, v148
	v_lshlrev_b32_e32 v111, 16, v149
	v_and_b32_e32 v114, 0xffff0000, v150
	v_add_f32_e32 v109, 1.0, v109
	v_div_scale_f32 v117, s[2:3], v109, v109, 1.0
	v_rcp_f32_e32 v118, v117
	v_lshlrev_b32_e32 v115, 16, v151
	v_and_b32_e32 v108, 0xffff0000, v151
	v_fma_f32 v119, -v117, v118, 1.0
	v_fmac_f32_e32 v118, v119, v118
	v_div_scale_f32 v119, vcc, 1.0, v109, 1.0
	v_mul_f32_e32 v120, v119, v118
	v_fma_f32 v121, -v117, v120, v119
	v_fmac_f32_e32 v120, v121, v118
	v_fma_f32 v117, -v117, v120, v119
	v_div_fmas_f32 v117, v117, v118, v120
	v_div_fixup_f32 v109, v117, v109, 1.0
	v_mul_f32_e32 v104, v104, v109
	v_mul_f32_e32 v109, 0xbfb8aa3b, v110
	v_exp_f32_e32 v109, v109
	s_nop 0
	v_add_f32_e32 v109, 1.0, v109
	v_div_scale_f32 v110, s[2:3], v109, v109, 1.0
	v_rcp_f32_e32 v117, v110
	s_nop 0
	v_fma_f32 v118, -v110, v117, 1.0
	v_fmac_f32_e32 v117, v118, v117
	v_div_scale_f32 v118, vcc, 1.0, v109, 1.0
	v_mul_f32_e32 v119, v118, v117
	v_fma_f32 v120, -v110, v119, v118
	v_fmac_f32_e32 v119, v120, v117
	v_fma_f32 v110, -v110, v119, v118
	v_div_fmas_f32 v110, v110, v117, v119
	v_div_fixup_f32 v109, v110, v109, 1.0
	v_mul_f32_e32 v105, v105, v109
	v_mul_f32_e32 v109, 0xbfb8aa3b, v111
	v_exp_f32_e32 v109, v109
	s_nop 0
	v_add_f32_e32 v109, 1.0, v109
	v_div_scale_f32 v110, s[2:3], v109, v109, 1.0
	v_rcp_f32_e32 v111, v110
	s_nop 0
	v_fma_f32 v117, -v110, v111, 1.0
	v_fmac_f32_e32 v111, v117, v111
	v_div_scale_f32 v117, vcc, 1.0, v109, 1.0
	v_mul_f32_e32 v118, v117, v111
	v_fma_f32 v119, -v110, v118, v117
	v_fmac_f32_e32 v118, v119, v111
	v_fma_f32 v110, -v110, v118, v117
	v_div_fmas_f32 v110, v110, v111, v118
	v_div_fixup_f32 v109, v110, v109, 1.0
	v_mul_f32_e32 v106, v106, v109
	v_mul_f32_e32 v109, 0xbfb8aa3b, v112
	v_exp_f32_e32 v109, v109
	s_nop 0
	v_add_f32_e32 v109, 1.0, v109
	v_div_scale_f32 v110, s[2:3], v109, v109, 1.0
	v_rcp_f32_e32 v111, v110
	s_nop 0
	v_fma_f32 v112, -v110, v111, 1.0
	v_fmac_f32_e32 v111, v112, v111
	v_div_scale_f32 v112, vcc, 1.0, v109, 1.0
	v_mul_f32_e32 v117, v112, v111
	v_fma_f32 v118, -v110, v117, v112
	v_fmac_f32_e32 v117, v118, v111
	v_fma_f32 v110, -v110, v117, v112
	v_div_fmas_f32 v110, v110, v111, v117
	v_div_fixup_f32 v109, v110, v109, 1.0
	v_mul_f32_e32 v107, v107, v109
	v_mul_f32_e32 v109, 0xbfb8aa3b, v113
	v_exp_f32_e32 v109, v109
	s_nop 0
	v_add_f32_e32 v109, 1.0, v109
	v_div_scale_f32 v110, s[2:3], v109, v109, 1.0
	v_rcp_f32_e32 v111, v110
	s_nop 0
	v_fma_f32 v112, -v110, v111, 1.0
	v_fmac_f32_e32 v111, v112, v111
	v_div_scale_f32 v112, vcc, 1.0, v109, 1.0
	v_mul_f32_e32 v113, v112, v111
	v_fma_f32 v117, -v110, v113, v112
	v_fmac_f32_e32 v113, v117, v111
	v_fma_f32 v110, -v110, v113, v112
	v_div_fmas_f32 v110, v110, v111, v113
	v_div_fixup_f32 v109, v110, v109, 1.0
	v_mul_f32_e32 v109, v100, v109
	v_mul_f32_e32 v100, 0xbfb8aa3b, v114
	v_exp_f32_e32 v100, v100
	s_nop 0
	v_add_f32_e32 v100, 1.0, v100
	v_div_scale_f32 v110, s[2:3], v100, v100, 1.0
	v_rcp_f32_e32 v111, v110
	s_nop 0
	v_fma_f32 v112, -v110, v111, 1.0
	v_fmac_f32_e32 v111, v112, v111
	v_div_scale_f32 v112, vcc, 1.0, v100, 1.0
	v_mul_f32_e32 v113, v112, v111
	v_fma_f32 v114, -v110, v113, v112
	v_fmac_f32_e32 v113, v114, v111
	v_fma_f32 v110, -v110, v113, v112
	v_div_fmas_f32 v110, v110, v111, v113
	v_div_fixup_f32 v100, v110, v100, 1.0
	v_mul_f32_e32 v110, v101, v100
	v_mul_f32_e32 v100, 0xbfb8aa3b, v115
	v_exp_f32_e32 v100, v100
	s_nop 0
	v_add_f32_e32 v100, 1.0, v100
	v_div_scale_f32 v101, s[2:3], v100, v100, 1.0
	v_rcp_f32_e32 v111, v101
	s_nop 0
	v_fma_f32 v112, -v101, v111, 1.0
	v_fmac_f32_e32 v111, v112, v111
	v_div_scale_f32 v112, vcc, 1.0, v100, 1.0
	v_mul_f32_e32 v113, v112, v111
	v_fma_f32 v114, -v101, v113, v112
	v_fmac_f32_e32 v113, v114, v111
	v_fma_f32 v101, -v101, v113, v112
	v_div_fmas_f32 v101, v101, v111, v113
	v_div_fixup_f32 v100, v101, v100, 1.0
	v_mul_f32_e32 v111, v102, v100
	v_mul_f32_e32 v100, 0xbfb8aa3b, v108
	v_exp_f32_e32 v100, v100
	s_nop 0
	v_add_f32_e32 v100, 1.0, v100
	v_div_scale_f32 v101, s[2:3], v100, v100, 1.0
	v_rcp_f32_e32 v102, v101
	s_nop 0
	v_fma_f32 v108, -v101, v102, 1.0
	v_fmac_f32_e32 v102, v108, v102
	v_div_scale_f32 v108, vcc, 1.0, v100, 1.0
	v_mul_f32_e32 v112, v108, v102
	v_fma_f32 v113, -v101, v112, v108
	v_fmac_f32_e32 v112, v113, v102
	v_fma_f32 v101, -v101, v112, v108
	v_div_fmas_f32 v101, v101, v102, v112
	v_div_fixup_f32 v100, v101, v100, 1.0
	v_mul_f32_e32 v103, v103, v100
	v_cvt_pk_bf16_f32 v100, v104, v105
	v_cvt_pk_bf16_f32 v101, v106, v107
	v_cvt_pk_bf16_f32 v102, v109, v110
	v_cvt_pk_bf16_f32 v103, v111, v103
	buffer_store_dwordx4 v[100:103], v116, s[80:83], 0 offen offset:256 sc1
	s_waitcnt vmcnt(7)
	v_lshlrev_b32_e32 v104, 16, v145
	v_and_b32_e32 v105, 0xffff0000, v145
	v_lshlrev_b32_e32 v102, 16, v144
	v_mul_f32_e32 v102, 0xbfb8aa3b, v102
	v_exp_f32_e32 v102, v102
	v_and_b32_e32 v103, 0xffff0000, v144
	v_lshlrev_b32_e32 v106, 16, v146
	v_and_b32_e32 v107, 0xffff0000, v146
	v_add_f32_e32 v102, 1.0, v102
	v_div_scale_f32 v109, s[2:3], v102, v102, 1.0
	v_rcp_f32_e32 v110, v109
	v_lshlrev_b32_e32 v108, 16, v147
	v_and_b32_e32 v101, 0xffff0000, v147
	v_add_u32_e32 v100, 0x20000, v1
	v_fma_f32 v111, -v109, v110, 1.0
	v_fmac_f32_e32 v110, v111, v110
	v_div_scale_f32 v111, vcc, 1.0, v102, 1.0
	v_mul_f32_e32 v112, v111, v110
	v_fma_f32 v113, -v109, v112, v111
	v_fmac_f32_e32 v112, v113, v110
	v_fma_f32 v109, -v109, v112, v111
	v_div_fmas_f32 v109, v109, v110, v112
	v_div_fixup_f32 v102, v109, v102, 1.0
	v_mul_f32_e32 v96, v96, v102
	v_mul_f32_e32 v102, 0xbfb8aa3b, v103
	v_exp_f32_e32 v102, v102
	s_nop 0
	v_add_f32_e32 v102, 1.0, v102
	v_div_scale_f32 v103, s[2:3], v102, v102, 1.0
	v_rcp_f32_e32 v109, v103
	s_nop 0
	v_fma_f32 v110, -v103, v109, 1.0
	v_fmac_f32_e32 v109, v110, v109
	v_div_scale_f32 v110, vcc, 1.0, v102, 1.0
	v_mul_f32_e32 v111, v110, v109
	v_fma_f32 v112, -v103, v111, v110
	v_fmac_f32_e32 v111, v112, v109
	v_fma_f32 v103, -v103, v111, v110
	v_div_fmas_f32 v103, v103, v109, v111
	v_div_fixup_f32 v102, v103, v102, 1.0
	v_mul_f32_e32 v97, v97, v102
	v_mul_f32_e32 v102, 0xbfb8aa3b, v104
	v_exp_f32_e32 v102, v102
	s_nop 0
	v_add_f32_e32 v102, 1.0, v102
	v_div_scale_f32 v103, s[2:3], v102, v102, 1.0
	v_rcp_f32_e32 v104, v103
	s_nop 0
	v_fma_f32 v109, -v103, v104, 1.0
	v_fmac_f32_e32 v104, v109, v104
	v_div_scale_f32 v109, vcc, 1.0, v102, 1.0
	v_mul_f32_e32 v110, v109, v104
	v_fma_f32 v111, -v103, v110, v109
	v_fmac_f32_e32 v110, v111, v104
	v_fma_f32 v103, -v103, v110, v109
	v_div_fmas_f32 v103, v103, v104, v110
	v_div_fixup_f32 v102, v103, v102, 1.0
	v_mul_f32_e32 v98, v98, v102
	v_mul_f32_e32 v102, 0xbfb8aa3b, v105
	v_exp_f32_e32 v102, v102
	s_nop 0
	v_add_f32_e32 v102, 1.0, v102
	v_div_scale_f32 v103, s[2:3], v102, v102, 1.0
	v_rcp_f32_e32 v104, v103
	s_nop 0
	v_fma_f32 v105, -v103, v104, 1.0
	v_fmac_f32_e32 v104, v105, v104
	v_div_scale_f32 v105, vcc, 1.0, v102, 1.0
	v_mul_f32_e32 v109, v105, v104
	v_fma_f32 v110, -v103, v109, v105
	v_fmac_f32_e32 v109, v110, v104
	v_fma_f32 v103, -v103, v109, v105
	v_div_fmas_f32 v103, v103, v104, v109
	v_div_fixup_f32 v102, v103, v102, 1.0
	v_mul_f32_e32 v99, v99, v102
	v_mul_f32_e32 v102, 0xbfb8aa3b, v106
	v_exp_f32_e32 v102, v102
	s_nop 0
	v_add_f32_e32 v102, 1.0, v102
	v_div_scale_f32 v103, s[2:3], v102, v102, 1.0
	v_rcp_f32_e32 v104, v103
	s_nop 0
	v_fma_f32 v105, -v103, v104, 1.0
	v_fmac_f32_e32 v104, v105, v104
	v_div_scale_f32 v105, vcc, 1.0, v102, 1.0
	v_mul_f32_e32 v106, v105, v104
	v_fma_f32 v109, -v103, v106, v105
	v_fmac_f32_e32 v106, v109, v104
	v_fma_f32 v103, -v103, v106, v105
	v_div_fmas_f32 v103, v103, v104, v106
	v_div_fixup_f32 v102, v103, v102, 1.0
	v_mul_f32_e32 v102, v92, v102
	v_mul_f32_e32 v92, 0xbfb8aa3b, v107
	v_exp_f32_e32 v92, v92
	s_nop 0
	v_add_f32_e32 v92, 1.0, v92
	v_div_scale_f32 v103, s[2:3], v92, v92, 1.0
	v_rcp_f32_e32 v104, v103
	s_nop 0
	v_fma_f32 v105, -v103, v104, 1.0
	v_fmac_f32_e32 v104, v105, v104
	v_div_scale_f32 v105, vcc, 1.0, v92, 1.0
	v_mul_f32_e32 v106, v105, v104
	v_fma_f32 v107, -v103, v106, v105
	v_fmac_f32_e32 v106, v107, v104
	v_fma_f32 v103, -v103, v106, v105
	v_div_fmas_f32 v103, v103, v104, v106
	v_div_fixup_f32 v92, v103, v92, 1.0
	v_mul_f32_e32 v103, v93, v92
	v_mul_f32_e32 v92, 0xbfb8aa3b, v108
	v_exp_f32_e32 v92, v92
	s_nop 0
	v_add_f32_e32 v92, 1.0, v92
	v_div_scale_f32 v93, s[2:3], v92, v92, 1.0
	v_rcp_f32_e32 v104, v93
	s_nop 0
	v_fma_f32 v105, -v93, v104, 1.0
	v_fmac_f32_e32 v104, v105, v104
	v_div_scale_f32 v105, vcc, 1.0, v92, 1.0
	v_mul_f32_e32 v106, v105, v104
	v_fma_f32 v107, -v93, v106, v105
	v_fmac_f32_e32 v106, v107, v104
	v_fma_f32 v93, -v93, v106, v105
	v_div_fmas_f32 v93, v93, v104, v106
	v_div_fixup_f32 v92, v93, v92, 1.0
	v_mul_f32_e32 v104, v94, v92
	v_mul_f32_e32 v92, 0xbfb8aa3b, v101
	v_exp_f32_e32 v92, v92
	s_nop 0
	v_add_f32_e32 v92, 1.0, v92
	v_div_scale_f32 v93, s[2:3], v92, v92, 1.0
	v_rcp_f32_e32 v94, v93
	s_nop 0
	v_fma_f32 v101, -v93, v94, 1.0
	v_fmac_f32_e32 v94, v101, v94
	v_div_scale_f32 v101, vcc, 1.0, v92, 1.0
	v_mul_f32_e32 v105, v101, v94
	v_fma_f32 v106, -v93, v105, v101
	v_fmac_f32_e32 v105, v106, v94
	v_fma_f32 v93, -v93, v105, v101
	v_div_fmas_f32 v93, v93, v94, v105
	v_div_fixup_f32 v92, v93, v92, 1.0
	v_mul_f32_e32 v95, v95, v92
	v_cvt_pk_bf16_f32 v92, v96, v97
	v_cvt_pk_bf16_f32 v93, v98, v99
	v_cvt_pk_bf16_f32 v94, v102, v103
	v_cvt_pk_bf16_f32 v95, v104, v95
	buffer_store_dwordx4 v[92:95], v100, s[80:83], 0 offen sc1
	s_waitcnt vmcnt(7)
	v_and_b32_e32 v96, 0xffff0000, v141
	v_lshlrev_b32_e32 v97, 16, v142
	v_lshlrev_b32_e32 v93, 16, v140
	v_mul_f32_e32 v93, 0xbfb8aa3b, v93
	v_exp_f32_e32 v93, v93
	v_and_b32_e32 v94, 0xffff0000, v140
	v_lshlrev_b32_e32 v95, 16, v141
	v_and_b32_e32 v98, 0xffff0000, v142
	v_add_f32_e32 v93, 1.0, v93
	v_div_scale_f32 v101, s[2:3], v93, v93, 1.0
	v_rcp_f32_e32 v102, v101
	v_lshlrev_b32_e32 v99, 16, v143
	v_and_b32_e32 v92, 0xffff0000, v143
	v_fma_f32 v103, -v101, v102, 1.0
	v_fmac_f32_e32 v102, v103, v102
	v_div_scale_f32 v103, vcc, 1.0, v93, 1.0
	v_mul_f32_e32 v104, v103, v102
	v_fma_f32 v105, -v101, v104, v103
	v_fmac_f32_e32 v104, v105, v102
	v_fma_f32 v101, -v101, v104, v103
	v_div_fmas_f32 v101, v101, v102, v104
	v_div_fixup_f32 v93, v101, v93, 1.0
	v_mul_f32_e32 v88, v88, v93
	v_mul_f32_e32 v93, 0xbfb8aa3b, v94
	v_exp_f32_e32 v93, v93
	s_nop 0
	v_add_f32_e32 v93, 1.0, v93
	v_div_scale_f32 v94, s[2:3], v93, v93, 1.0
	v_rcp_f32_e32 v101, v94
	s_nop 0
	v_fma_f32 v102, -v94, v101, 1.0
	v_fmac_f32_e32 v101, v102, v101
	v_div_scale_f32 v102, vcc, 1.0, v93, 1.0
	v_mul_f32_e32 v103, v102, v101
	v_fma_f32 v104, -v94, v103, v102
	v_fmac_f32_e32 v103, v104, v101
	v_fma_f32 v94, -v94, v103, v102
	v_div_fmas_f32 v94, v94, v101, v103
	v_div_fixup_f32 v93, v94, v93, 1.0
	v_mul_f32_e32 v89, v89, v93
	v_mul_f32_e32 v93, 0xbfb8aa3b, v95
	v_exp_f32_e32 v93, v93
	s_nop 0
	v_add_f32_e32 v93, 1.0, v93
	v_div_scale_f32 v94, s[2:3], v93, v93, 1.0
	v_rcp_f32_e32 v95, v94
	s_nop 0
	v_fma_f32 v101, -v94, v95, 1.0
	v_fmac_f32_e32 v95, v101, v95
	v_div_scale_f32 v101, vcc, 1.0, v93, 1.0
	v_mul_f32_e32 v102, v101, v95
	v_fma_f32 v103, -v94, v102, v101
	v_fmac_f32_e32 v102, v103, v95
	v_fma_f32 v94, -v94, v102, v101
	v_div_fmas_f32 v94, v94, v95, v102
	v_div_fixup_f32 v93, v94, v93, 1.0
	v_mul_f32_e32 v90, v90, v93
	v_mul_f32_e32 v93, 0xbfb8aa3b, v96
	v_exp_f32_e32 v93, v93
	s_nop 0
	v_add_f32_e32 v93, 1.0, v93
	v_div_scale_f32 v94, s[2:3], v93, v93, 1.0
	v_rcp_f32_e32 v95, v94
	s_nop 0
	v_fma_f32 v96, -v94, v95, 1.0
	v_fmac_f32_e32 v95, v96, v95
	v_div_scale_f32 v96, vcc, 1.0, v93, 1.0
	v_mul_f32_e32 v101, v96, v95
	v_fma_f32 v102, -v94, v101, v96
	v_fmac_f32_e32 v101, v102, v95
	v_fma_f32 v94, -v94, v101, v96
	v_div_fmas_f32 v94, v94, v95, v101
	v_div_fixup_f32 v93, v94, v93, 1.0
	v_mul_f32_e32 v91, v91, v93
	v_mul_f32_e32 v93, 0xbfb8aa3b, v97
	v_exp_f32_e32 v93, v93
	s_nop 0
	v_add_f32_e32 v93, 1.0, v93
	v_div_scale_f32 v94, s[2:3], v93, v93, 1.0
	v_rcp_f32_e32 v95, v94
	s_nop 0
	v_fma_f32 v96, -v94, v95, 1.0
	v_fmac_f32_e32 v95, v96, v95
	v_div_scale_f32 v96, vcc, 1.0, v93, 1.0
	v_mul_f32_e32 v97, v96, v95
	v_fma_f32 v101, -v94, v97, v96
	v_fmac_f32_e32 v97, v101, v95
	v_fma_f32 v94, -v94, v97, v96
	v_div_fmas_f32 v94, v94, v95, v97
	v_div_fixup_f32 v93, v94, v93, 1.0
	v_mul_f32_e32 v93, v84, v93
	v_mul_f32_e32 v84, 0xbfb8aa3b, v98
	v_exp_f32_e32 v84, v84
	s_nop 0
	v_add_f32_e32 v84, 1.0, v84
	v_div_scale_f32 v94, s[2:3], v84, v84, 1.0
	v_rcp_f32_e32 v95, v94
	s_nop 0
	v_fma_f32 v96, -v94, v95, 1.0
	v_fmac_f32_e32 v95, v96, v95
	v_div_scale_f32 v96, vcc, 1.0, v84, 1.0
	v_mul_f32_e32 v97, v96, v95
	v_fma_f32 v98, -v94, v97, v96
	v_fmac_f32_e32 v97, v98, v95
	v_fma_f32 v94, -v94, v97, v96
	v_div_fmas_f32 v94, v94, v95, v97
	v_div_fixup_f32 v84, v94, v84, 1.0
	v_mul_f32_e32 v94, v85, v84
	v_mul_f32_e32 v84, 0xbfb8aa3b, v99
	v_exp_f32_e32 v84, v84
	s_nop 0
	v_add_f32_e32 v84, 1.0, v84
	v_div_scale_f32 v85, s[2:3], v84, v84, 1.0
	v_rcp_f32_e32 v95, v85
	s_nop 0
	v_fma_f32 v96, -v85, v95, 1.0
	v_fmac_f32_e32 v95, v96, v95
	v_div_scale_f32 v96, vcc, 1.0, v84, 1.0
	v_mul_f32_e32 v97, v96, v95
	v_fma_f32 v98, -v85, v97, v96
	v_fmac_f32_e32 v97, v98, v95
	v_fma_f32 v85, -v85, v97, v96
	v_div_fmas_f32 v85, v85, v95, v97
	v_div_fixup_f32 v84, v85, v84, 1.0
	v_mul_f32_e32 v95, v86, v84
	v_mul_f32_e32 v84, 0xbfb8aa3b, v92
	v_exp_f32_e32 v84, v84
	s_nop 0
	v_add_f32_e32 v84, 1.0, v84
	v_div_scale_f32 v85, s[2:3], v84, v84, 1.0
	v_rcp_f32_e32 v86, v85
	s_nop 0
	v_fma_f32 v92, -v85, v86, 1.0
	v_fmac_f32_e32 v86, v92, v86
	v_div_scale_f32 v92, vcc, 1.0, v84, 1.0
	v_mul_f32_e32 v96, v92, v86
	v_fma_f32 v97, -v85, v96, v92
	v_fmac_f32_e32 v96, v97, v86
	v_fma_f32 v85, -v85, v96, v92
	v_div_fmas_f32 v85, v85, v86, v96
	v_div_fixup_f32 v84, v85, v84, 1.0
	v_mul_f32_e32 v87, v87, v84
	v_cvt_pk_bf16_f32 v84, v88, v89
	v_cvt_pk_bf16_f32 v85, v90, v91
	v_cvt_pk_bf16_f32 v86, v93, v94
	v_cvt_pk_bf16_f32 v87, v95, v87
	buffer_store_dwordx4 v[84:87], v100, s[80:83], 0 offen offset:256 sc1
	s_waitcnt vmcnt(7)
	v_lshlrev_b32_e32 v88, 16, v137
	v_and_b32_e32 v89, 0xffff0000, v137
	v_lshlrev_b32_e32 v86, 16, v136
	v_mul_f32_e32 v86, 0xbfb8aa3b, v86
	v_exp_f32_e32 v86, v86
	v_and_b32_e32 v87, 0xffff0000, v136
	v_lshlrev_b32_e32 v90, 16, v138
	v_and_b32_e32 v91, 0xffff0000, v138
	v_add_f32_e32 v86, 1.0, v86
	v_div_scale_f32 v93, s[2:3], v86, v86, 1.0
	v_rcp_f32_e32 v94, v93
	v_lshlrev_b32_e32 v92, 16, v139
	v_and_b32_e32 v85, 0xffff0000, v139
	v_add_u32_e32 v84, 0x30000, v1
	v_fma_f32 v95, -v93, v94, 1.0
	v_fmac_f32_e32 v94, v95, v94
	v_div_scale_f32 v95, vcc, 1.0, v86, 1.0
	v_mul_f32_e32 v96, v95, v94
	v_fma_f32 v97, -v93, v96, v95
	v_fmac_f32_e32 v96, v97, v94
	v_fma_f32 v93, -v93, v96, v95
	v_div_fmas_f32 v93, v93, v94, v96
	v_div_fixup_f32 v86, v93, v86, 1.0
	v_mul_f32_e32 v80, v80, v86
	v_mul_f32_e32 v86, 0xbfb8aa3b, v87
	v_exp_f32_e32 v86, v86
	s_nop 0
	v_add_f32_e32 v86, 1.0, v86
	v_div_scale_f32 v87, s[2:3], v86, v86, 1.0
	v_rcp_f32_e32 v93, v87
	s_nop 0
	v_fma_f32 v94, -v87, v93, 1.0
	v_fmac_f32_e32 v93, v94, v93
	v_div_scale_f32 v94, vcc, 1.0, v86, 1.0
	v_mul_f32_e32 v95, v94, v93
	v_fma_f32 v96, -v87, v95, v94
	v_fmac_f32_e32 v95, v96, v93
	v_fma_f32 v87, -v87, v95, v94
	v_div_fmas_f32 v87, v87, v93, v95
	v_div_fixup_f32 v86, v87, v86, 1.0
	v_mul_f32_e32 v81, v81, v86
	v_mul_f32_e32 v86, 0xbfb8aa3b, v88
	v_exp_f32_e32 v86, v86
	s_nop 0
	v_add_f32_e32 v86, 1.0, v86
	v_div_scale_f32 v87, s[2:3], v86, v86, 1.0
	v_rcp_f32_e32 v88, v87
	s_nop 0
	v_fma_f32 v93, -v87, v88, 1.0
	v_fmac_f32_e32 v88, v93, v88
	v_div_scale_f32 v93, vcc, 1.0, v86, 1.0
	v_mul_f32_e32 v94, v93, v88
	v_fma_f32 v95, -v87, v94, v93
	v_fmac_f32_e32 v94, v95, v88
	v_fma_f32 v87, -v87, v94, v93
	v_div_fmas_f32 v87, v87, v88, v94
	v_div_fixup_f32 v86, v87, v86, 1.0
	v_mul_f32_e32 v82, v82, v86
	v_mul_f32_e32 v86, 0xbfb8aa3b, v89
	v_exp_f32_e32 v86, v86
	s_nop 0
	v_add_f32_e32 v86, 1.0, v86
	v_div_scale_f32 v87, s[2:3], v86, v86, 1.0
	v_rcp_f32_e32 v88, v87
	s_nop 0
	v_fma_f32 v89, -v87, v88, 1.0
	v_fmac_f32_e32 v88, v89, v88
	v_div_scale_f32 v89, vcc, 1.0, v86, 1.0
	v_mul_f32_e32 v93, v89, v88
	v_fma_f32 v94, -v87, v93, v89
	v_fmac_f32_e32 v93, v94, v88
	v_fma_f32 v87, -v87, v93, v89
	v_div_fmas_f32 v87, v87, v88, v93
	v_div_fixup_f32 v86, v87, v86, 1.0
	v_mul_f32_e32 v83, v83, v86
	v_mul_f32_e32 v86, 0xbfb8aa3b, v90
	v_exp_f32_e32 v86, v86
	s_nop 0
	v_add_f32_e32 v86, 1.0, v86
	v_div_scale_f32 v87, s[2:3], v86, v86, 1.0
	v_rcp_f32_e32 v88, v87
	s_nop 0
	v_fma_f32 v89, -v87, v88, 1.0
	v_fmac_f32_e32 v88, v89, v88
	v_div_scale_f32 v89, vcc, 1.0, v86, 1.0
	v_mul_f32_e32 v90, v89, v88
	v_fma_f32 v93, -v87, v90, v89
	v_fmac_f32_e32 v90, v93, v88
	v_fma_f32 v87, -v87, v90, v89
	v_div_fmas_f32 v87, v87, v88, v90
	v_div_fixup_f32 v86, v87, v86, 1.0
	v_mul_f32_e32 v86, v76, v86
	v_mul_f32_e32 v76, 0xbfb8aa3b, v91
	v_exp_f32_e32 v76, v76
	s_nop 0
	v_add_f32_e32 v76, 1.0, v76
	v_div_scale_f32 v87, s[2:3], v76, v76, 1.0
	v_rcp_f32_e32 v88, v87
	s_nop 0
	v_fma_f32 v89, -v87, v88, 1.0
	v_fmac_f32_e32 v88, v89, v88
	v_div_scale_f32 v89, vcc, 1.0, v76, 1.0
	v_mul_f32_e32 v90, v89, v88
	v_fma_f32 v91, -v87, v90, v89
	v_fmac_f32_e32 v90, v91, v88
	v_fma_f32 v87, -v87, v90, v89
	v_div_fmas_f32 v87, v87, v88, v90
	v_div_fixup_f32 v76, v87, v76, 1.0
	v_mul_f32_e32 v87, v77, v76
	v_mul_f32_e32 v76, 0xbfb8aa3b, v92
	v_exp_f32_e32 v76, v76
	s_nop 0
	v_add_f32_e32 v76, 1.0, v76
	v_div_scale_f32 v77, s[2:3], v76, v76, 1.0
	v_rcp_f32_e32 v88, v77
	s_nop 0
	v_fma_f32 v89, -v77, v88, 1.0
	v_fmac_f32_e32 v88, v89, v88
	v_div_scale_f32 v89, vcc, 1.0, v76, 1.0
	v_mul_f32_e32 v90, v89, v88
	v_fma_f32 v91, -v77, v90, v89
	v_fmac_f32_e32 v90, v91, v88
	v_fma_f32 v77, -v77, v90, v89
	v_div_fmas_f32 v77, v77, v88, v90
	v_div_fixup_f32 v76, v77, v76, 1.0
	v_mul_f32_e32 v88, v78, v76
	v_mul_f32_e32 v76, 0xbfb8aa3b, v85
	v_exp_f32_e32 v76, v76
	s_nop 0
	v_add_f32_e32 v76, 1.0, v76
	v_div_scale_f32 v77, s[2:3], v76, v76, 1.0
	v_rcp_f32_e32 v78, v77
	s_nop 0
	v_fma_f32 v85, -v77, v78, 1.0
	v_fmac_f32_e32 v78, v85, v78
	v_div_scale_f32 v85, vcc, 1.0, v76, 1.0
	v_mul_f32_e32 v89, v85, v78
	v_fma_f32 v90, -v77, v89, v85
	v_fmac_f32_e32 v89, v90, v78
	v_fma_f32 v77, -v77, v89, v85
	v_div_fmas_f32 v77, v77, v78, v89
	v_div_fixup_f32 v76, v77, v76, 1.0
	v_mul_f32_e32 v79, v79, v76
	v_cvt_pk_bf16_f32 v76, v80, v81
	v_cvt_pk_bf16_f32 v77, v82, v83
	v_cvt_pk_bf16_f32 v78, v86, v87
	v_cvt_pk_bf16_f32 v79, v88, v79
	buffer_store_dwordx4 v[76:79], v84, s[80:83], 0 offen sc1
	s_waitcnt vmcnt(7)
	v_and_b32_e32 v80, 0xffff0000, v133
	v_lshlrev_b32_e32 v81, 16, v134
	v_lshlrev_b32_e32 v77, 16, v132
	v_mul_f32_e32 v77, 0xbfb8aa3b, v77
	v_exp_f32_e32 v77, v77
	v_and_b32_e32 v78, 0xffff0000, v132
	v_lshlrev_b32_e32 v79, 16, v133
	v_and_b32_e32 v82, 0xffff0000, v134
	v_add_f32_e32 v77, 1.0, v77
	v_div_scale_f32 v85, s[2:3], v77, v77, 1.0
	v_rcp_f32_e32 v86, v85
	v_lshlrev_b32_e32 v83, 16, v135
	v_and_b32_e32 v76, 0xffff0000, v135
	v_fma_f32 v87, -v85, v86, 1.0
	v_fmac_f32_e32 v86, v87, v86
	v_div_scale_f32 v87, vcc, 1.0, v77, 1.0
	v_mul_f32_e32 v88, v87, v86
	v_fma_f32 v89, -v85, v88, v87
	v_fmac_f32_e32 v88, v89, v86
	v_fma_f32 v85, -v85, v88, v87
	v_div_fmas_f32 v85, v85, v86, v88
	v_div_fixup_f32 v77, v85, v77, 1.0
	v_mul_f32_e32 v72, v72, v77
	v_mul_f32_e32 v77, 0xbfb8aa3b, v78
	v_exp_f32_e32 v77, v77
	s_nop 0
	v_add_f32_e32 v77, 1.0, v77
	v_div_scale_f32 v78, s[2:3], v77, v77, 1.0
	v_rcp_f32_e32 v85, v78
	s_nop 0
	v_fma_f32 v86, -v78, v85, 1.0
	v_fmac_f32_e32 v85, v86, v85
	v_div_scale_f32 v86, vcc, 1.0, v77, 1.0
	v_mul_f32_e32 v87, v86, v85
	v_fma_f32 v88, -v78, v87, v86
	v_fmac_f32_e32 v87, v88, v85
	v_fma_f32 v78, -v78, v87, v86
	v_div_fmas_f32 v78, v78, v85, v87
	v_div_fixup_f32 v77, v78, v77, 1.0
	v_mul_f32_e32 v73, v73, v77
	v_mul_f32_e32 v77, 0xbfb8aa3b, v79
	v_exp_f32_e32 v77, v77
	s_nop 0
	v_add_f32_e32 v77, 1.0, v77
	v_div_scale_f32 v78, s[2:3], v77, v77, 1.0
	v_rcp_f32_e32 v79, v78
	s_nop 0
	v_fma_f32 v85, -v78, v79, 1.0
	v_fmac_f32_e32 v79, v85, v79
	v_div_scale_f32 v85, vcc, 1.0, v77, 1.0
	v_mul_f32_e32 v86, v85, v79
	v_fma_f32 v87, -v78, v86, v85
	v_fmac_f32_e32 v86, v87, v79
	v_fma_f32 v78, -v78, v86, v85
	v_div_fmas_f32 v78, v78, v79, v86
	v_div_fixup_f32 v77, v78, v77, 1.0
	v_mul_f32_e32 v74, v74, v77
	v_mul_f32_e32 v77, 0xbfb8aa3b, v80
	v_exp_f32_e32 v77, v77
	s_nop 0
	v_add_f32_e32 v77, 1.0, v77
	v_div_scale_f32 v78, s[2:3], v77, v77, 1.0
	v_rcp_f32_e32 v79, v78
	s_nop 0
	v_fma_f32 v80, -v78, v79, 1.0
	v_fmac_f32_e32 v79, v80, v79
	v_div_scale_f32 v80, vcc, 1.0, v77, 1.0
	v_mul_f32_e32 v85, v80, v79
	v_fma_f32 v86, -v78, v85, v80
	v_fmac_f32_e32 v85, v86, v79
	v_fma_f32 v78, -v78, v85, v80
	v_div_fmas_f32 v78, v78, v79, v85
	v_div_fixup_f32 v77, v78, v77, 1.0
	v_mul_f32_e32 v75, v75, v77
	v_mul_f32_e32 v77, 0xbfb8aa3b, v81
	v_exp_f32_e32 v77, v77
	s_nop 0
	v_add_f32_e32 v77, 1.0, v77
	v_div_scale_f32 v78, s[2:3], v77, v77, 1.0
	v_rcp_f32_e32 v79, v78
	s_nop 0
	v_fma_f32 v80, -v78, v79, 1.0
	v_fmac_f32_e32 v79, v80, v79
	v_div_scale_f32 v80, vcc, 1.0, v77, 1.0
	v_mul_f32_e32 v81, v80, v79
	v_fma_f32 v85, -v78, v81, v80
	v_fmac_f32_e32 v81, v85, v79
	v_fma_f32 v78, -v78, v81, v80
	v_div_fmas_f32 v78, v78, v79, v81
	v_div_fixup_f32 v77, v78, v77, 1.0
	v_mul_f32_e32 v77, v68, v77
	v_mul_f32_e32 v68, 0xbfb8aa3b, v82
	v_exp_f32_e32 v68, v68
	s_nop 0
	v_add_f32_e32 v68, 1.0, v68
	v_div_scale_f32 v78, s[2:3], v68, v68, 1.0
	v_rcp_f32_e32 v79, v78
	s_nop 0
	v_fma_f32 v80, -v78, v79, 1.0
	v_fmac_f32_e32 v79, v80, v79
	v_div_scale_f32 v80, vcc, 1.0, v68, 1.0
	v_mul_f32_e32 v81, v80, v79
	v_fma_f32 v82, -v78, v81, v80
	v_fmac_f32_e32 v81, v82, v79
	v_fma_f32 v78, -v78, v81, v80
	v_div_fmas_f32 v78, v78, v79, v81
	v_div_fixup_f32 v68, v78, v68, 1.0
	v_mul_f32_e32 v78, v69, v68
	v_mul_f32_e32 v68, 0xbfb8aa3b, v83
	v_exp_f32_e32 v68, v68
	s_nop 0
	v_add_f32_e32 v68, 1.0, v68
	v_div_scale_f32 v69, s[2:3], v68, v68, 1.0
	v_rcp_f32_e32 v79, v69
	s_nop 0
	v_fma_f32 v80, -v69, v79, 1.0
	v_fmac_f32_e32 v79, v80, v79
	v_div_scale_f32 v80, vcc, 1.0, v68, 1.0
	v_mul_f32_e32 v81, v80, v79
	v_fma_f32 v82, -v69, v81, v80
	v_fmac_f32_e32 v81, v82, v79
	v_fma_f32 v69, -v69, v81, v80
	v_div_fmas_f32 v69, v69, v79, v81
	v_div_fixup_f32 v68, v69, v68, 1.0
	v_mul_f32_e32 v79, v70, v68
	v_mul_f32_e32 v68, 0xbfb8aa3b, v76
	v_exp_f32_e32 v68, v68
	s_nop 0
	v_add_f32_e32 v68, 1.0, v68
	v_div_scale_f32 v69, s[2:3], v68, v68, 1.0
	v_rcp_f32_e32 v70, v69
	s_nop 0
	v_fma_f32 v76, -v69, v70, 1.0
	v_fmac_f32_e32 v70, v76, v70
	v_div_scale_f32 v76, vcc, 1.0, v68, 1.0
	v_mul_f32_e32 v80, v76, v70
	v_fma_f32 v81, -v69, v80, v76
	v_fmac_f32_e32 v80, v81, v70
	v_fma_f32 v69, -v69, v80, v76
	v_div_fmas_f32 v69, v69, v70, v80
	v_div_fixup_f32 v68, v69, v68, 1.0
	v_mul_f32_e32 v71, v71, v68
	v_cvt_pk_bf16_f32 v68, v72, v73
	v_cvt_pk_bf16_f32 v69, v74, v75
	v_cvt_pk_bf16_f32 v70, v77, v78
	v_cvt_pk_bf16_f32 v71, v79, v71
	buffer_store_dwordx4 v[68:71], v84, s[80:83], 0 offen offset:256 sc1
	s_nop 1
	s_waitcnt vmcnt(8)
	v_add_u32_e32 v68, 0xb0, v212
	v_mad_i64_i32 v[68:69], s[2:3], v68, s20, v[160:161]
	v_lshl_add_u64 v[68:69], v[68:69], 0, v[2:3]
	v_lshl_add_u64 v[68:69], v[68:69], 0, s[6:7]
	global_load_dwordx4 v[68:71], v[68:69], off offset:256
	v_mov_b64_e32 v[96:97], v[176:177]
	v_mov_b64_e32 v[98:99], v[178:179]
	v_mov_b64_e32 v[92:93], v[180:181]
	v_mov_b64_e32 v[94:95], v[182:183]
	v_mov_b64_e32 v[88:89], v[184:185]
	v_mov_b64_e32 v[90:91], v[186:187]
	v_mov_b64_e32 v[84:85], v[188:189]
	v_mov_b64_e32 v[86:87], v[190:191]
	v_mov_b64_e32 v[80:81], v[192:193]
	v_mov_b64_e32 v[82:83], v[194:195]
	v_mov_b64_e32 v[76:77], v[244:245]
	v_mov_b64_e32 v[78:79], v[246:247]
	v_mov_b64_e32 v[72:73], v[248:249]
	v_mov_b64_e32 v[74:75], v[250:251]
	v_lshlrev_b32_e32 v100, 16, v96
	v_lshlrev_b32_e32 v103, 16, v99
	v_and_b32_e32 v96, 0xffff0000, v96
	v_and_b32_e32 v3, 0xffff0000, v99
	v_mul_f32_e32 v99, 0xbfb8aa3b, v100
	v_exp_f32_e32 v99, v99
	v_mul_f32_e32 v96, 0xbfb8aa3b, v96
	v_exp_f32_e32 v96, v96
	v_lshlrev_b32_e32 v101, 16, v97
	v_add_f32_e32 v99, 1.0, v99
	v_div_scale_f32 v100, s[2:3], v99, v99, 1.0
	v_rcp_f32_e32 v104, v100
	v_add_f32_e32 v96, 1.0, v96
	v_and_b32_e32 v97, 0xffff0000, v97
	v_lshlrev_b32_e32 v102, 16, v98
	v_fma_f32 v105, -v100, v104, 1.0
	v_fmac_f32_e32 v104, v105, v104
	v_div_scale_f32 v105, vcc, 1.0, v99, 1.0
	v_mul_f32_e32 v106, v105, v104
	v_fma_f32 v107, -v100, v106, v105
	v_fmac_f32_e32 v106, v107, v104
	v_fma_f32 v100, -v100, v106, v105
	v_div_fmas_f32 v100, v100, v104, v106
	v_div_fixup_f32 v99, v100, v99, 1.0
	v_mul_f32_e32 v64, v64, v99
	v_div_scale_f32 v99, s[2:3], v96, v96, 1.0
	v_rcp_f32_e32 v100, v99
	v_and_b32_e32 v98, 0xffff0000, v98
	v_mul_f32_e32 v3, 0xbfb8aa3b, v3
	v_exp_f32_e32 v3, v3
	v_fma_f32 v104, -v99, v100, 1.0
	v_fmac_f32_e32 v100, v104, v100
	v_div_scale_f32 v104, vcc, 1.0, v96, 1.0
	v_mul_f32_e32 v105, v104, v100
	v_fma_f32 v106, -v99, v105, v104
	v_fmac_f32_e32 v105, v106, v100
	v_fma_f32 v99, -v99, v105, v104
	v_div_fmas_f32 v99, v99, v100, v105
	v_div_fixup_f32 v96, v99, v96, 1.0
	v_mul_f32_e32 v65, v65, v96
	v_mul_f32_e32 v96, 0xbfb8aa3b, v101
	v_exp_f32_e32 v96, v96
	v_add_f32_e32 v3, 1.0, v3
	v_add_u32_e32 v2, 0x80000, v1
	v_add_f32_e32 v96, 1.0, v96
	v_div_scale_f32 v99, s[2:3], v96, v96, 1.0
	v_rcp_f32_e32 v100, v99
	s_nop 0
	v_fma_f32 v101, -v99, v100, 1.0
	v_fmac_f32_e32 v100, v101, v100
	v_div_scale_f32 v101, vcc, 1.0, v96, 1.0
	v_mul_f32_e32 v104, v101, v100
	v_fma_f32 v105, -v99, v104, v101
	v_fmac_f32_e32 v104, v105, v100
	v_fma_f32 v99, -v99, v104, v101
	v_div_fmas_f32 v99, v99, v100, v104
	v_div_fixup_f32 v96, v99, v96, 1.0
	v_mul_f32_e32 v66, v66, v96
	v_mul_f32_e32 v96, 0xbfb8aa3b, v97
	v_exp_f32_e32 v96, v96
	s_nop 0
	v_add_f32_e32 v96, 1.0, v96
	v_div_scale_f32 v97, s[2:3], v96, v96, 1.0
	v_rcp_f32_e32 v99, v97
	s_nop 0
	v_fma_f32 v100, -v97, v99, 1.0
	v_fmac_f32_e32 v99, v100, v99
	v_div_scale_f32 v100, vcc, 1.0, v96, 1.0
	v_mul_f32_e32 v101, v100, v99
	v_fma_f32 v104, -v97, v101, v100
	v_fmac_f32_e32 v101, v104, v99
	v_fma_f32 v97, -v97, v101, v100
	v_div_fmas_f32 v97, v97, v99, v101
	v_div_fixup_f32 v96, v97, v96, 1.0
	v_mul_f32_e32 v67, v67, v96
	v_mul_f32_e32 v96, 0xbfb8aa3b, v102
	v_exp_f32_e32 v96, v96
	s_nop 0
	v_add_f32_e32 v96, 1.0, v96
	v_div_scale_f32 v97, s[2:3], v96, v96, 1.0
	v_rcp_f32_e32 v99, v97
	s_nop 0
	v_fma_f32 v100, -v97, v99, 1.0
	v_fmac_f32_e32 v99, v100, v99
	v_div_scale_f32 v100, vcc, 1.0, v96, 1.0
	v_mul_f32_e32 v101, v100, v99
	v_fma_f32 v102, -v97, v101, v100
	v_fmac_f32_e32 v101, v102, v99
	v_fma_f32 v97, -v97, v101, v100
	v_div_fmas_f32 v97, v97, v99, v101
	v_div_fixup_f32 v96, v97, v96, 1.0
	v_mul_f32_e32 v96, v60, v96
	v_mul_f32_e32 v60, 0xbfb8aa3b, v98
	v_exp_f32_e32 v60, v60
	s_nop 0
	v_add_f32_e32 v60, 1.0, v60
	v_div_scale_f32 v97, s[2:3], v60, v60, 1.0
	v_rcp_f32_e32 v98, v97
	s_nop 0
	v_fma_f32 v99, -v97, v98, 1.0
	v_fmac_f32_e32 v98, v99, v98
	v_div_scale_f32 v99, vcc, 1.0, v60, 1.0
	v_mul_f32_e32 v100, v99, v98
	v_fma_f32 v101, -v97, v100, v99
	v_fmac_f32_e32 v100, v101, v98
	v_fma_f32 v97, -v97, v100, v99
	v_div_fmas_f32 v97, v97, v98, v100
	v_div_fixup_f32 v60, v97, v60, 1.0
	v_mul_f32_e32 v97, v61, v60
	v_mul_f32_e32 v60, 0xbfb8aa3b, v103
	v_exp_f32_e32 v60, v60
	s_nop 0
	v_add_f32_e32 v60, 1.0, v60
	v_div_scale_f32 v61, s[2:3], v60, v60, 1.0
	v_rcp_f32_e32 v98, v61
	s_nop 0
	v_fma_f32 v99, -v61, v98, 1.0
	v_fmac_f32_e32 v98, v99, v98
	v_div_scale_f32 v99, vcc, 1.0, v60, 1.0
	v_mul_f32_e32 v100, v99, v98
	v_fma_f32 v101, -v61, v100, v99
	v_fmac_f32_e32 v100, v101, v98
	v_fma_f32 v61, -v61, v100, v99
	v_div_fmas_f32 v61, v61, v98, v100
	v_div_fixup_f32 v60, v61, v60, 1.0
	v_mul_f32_e32 v98, v62, v60
	v_div_scale_f32 v60, s[2:3], v3, v3, 1.0
	v_rcp_f32_e32 v61, v60
	s_nop 0
	v_fma_f32 v62, -v60, v61, 1.0
	v_fmac_f32_e32 v61, v62, v61
	v_div_scale_f32 v62, vcc, 1.0, v3, 1.0
	v_mul_f32_e32 v99, v62, v61
	v_fma_f32 v100, -v60, v99, v62
	v_fmac_f32_e32 v99, v100, v61
	v_fma_f32 v60, -v60, v99, v62
	v_div_fmas_f32 v60, v60, v61, v99
	v_div_fixup_f32 v3, v60, v3, 1.0
	v_cvt_pk_bf16_f32 v60, v64, v65
	v_mul_f32_e32 v3, v63, v3
	v_cvt_pk_bf16_f32 v61, v66, v67
	v_cvt_pk_bf16_f32 v62, v96, v97
	v_cvt_pk_bf16_f32 v63, v98, v3
	buffer_store_dwordx4 v[60:63], v2, s[80:83], 0 offen sc1
	v_lshlrev_b32_e32 v64, 16, v94
	v_and_b32_e32 v65, 0xffff0000, v94
	v_lshlrev_b32_e32 v60, 16, v92
	v_mul_f32_e32 v60, 0xbfb8aa3b, v60
	v_exp_f32_e32 v60, v60
	v_and_b32_e32 v61, 0xffff0000, v92
	v_lshlrev_b32_e32 v62, 16, v93
	v_and_b32_e32 v63, 0xffff0000, v93
	v_add_f32_e32 v60, 1.0, v60
	v_div_scale_f32 v67, s[2:3], v60, v60, 1.0
	v_rcp_f32_e32 v92, v67
	v_lshlrev_b32_e32 v66, 16, v95
	v_and_b32_e32 v3, 0xffff0000, v95
	v_mul_f32_e32 v3, 0xbfb8aa3b, v3
	v_fma_f32 v93, -v67, v92, 1.0
	v_fmac_f32_e32 v92, v93, v92
	v_div_scale_f32 v93, vcc, 1.0, v60, 1.0
	v_mul_f32_e32 v94, v93, v92
	v_fma_f32 v95, -v67, v94, v93
	v_fmac_f32_e32 v94, v95, v92
	v_fma_f32 v67, -v67, v94, v93
	v_div_fmas_f32 v67, v67, v92, v94
	v_div_fixup_f32 v60, v67, v60, 1.0
	v_mul_f32_e32 v56, v56, v60
	v_mul_f32_e32 v60, 0xbfb8aa3b, v61
	v_exp_f32_e32 v60, v60
	v_exp_f32_e32 v3, v3
	v_add_f32_e32 v60, 1.0, v60
	v_div_scale_f32 v61, s[2:3], v60, v60, 1.0
	v_rcp_f32_e32 v67, v61
	v_add_f32_e32 v3, 1.0, v3
	v_fma_f32 v92, -v61, v67, 1.0
	v_fmac_f32_e32 v67, v92, v67
	v_div_scale_f32 v92, vcc, 1.0, v60, 1.0
	v_mul_f32_e32 v93, v92, v67
	v_fma_f32 v94, -v61, v93, v92
	v_fmac_f32_e32 v93, v94, v67
	v_fma_f32 v61, -v61, v93, v92
	v_div_fmas_f32 v61, v61, v67, v93
	v_div_fixup_f32 v60, v61, v60, 1.0
	v_mul_f32_e32 v57, v57, v60
	v_mul_f32_e32 v60, 0xbfb8aa3b, v62
	v_exp_f32_e32 v60, v60
	s_nop 0
	v_add_f32_e32 v60, 1.0, v60
	v_div_scale_f32 v61, s[2:3], v60, v60, 1.0
	v_rcp_f32_e32 v62, v61
	s_nop 0
	v_fma_f32 v67, -v61, v62, 1.0
	v_fmac_f32_e32 v62, v67, v62
	v_div_scale_f32 v67, vcc, 1.0, v60, 1.0
	v_mul_f32_e32 v92, v67, v62
	v_fma_f32 v93, -v61, v92, v67
	v_fmac_f32_e32 v92, v93, v62
	v_fma_f32 v61, -v61, v92, v67
	v_div_fmas_f32 v61, v61, v62, v92
	v_div_fixup_f32 v60, v61, v60, 1.0
	v_mul_f32_e32 v58, v58, v60
	v_mul_f32_e32 v60, 0xbfb8aa3b, v63
	v_exp_f32_e32 v60, v60
	s_nop 0
	v_add_f32_e32 v60, 1.0, v60
	v_div_scale_f32 v61, s[2:3], v60, v60, 1.0
	v_rcp_f32_e32 v62, v61
	s_nop 0
	v_fma_f32 v63, -v61, v62, 1.0
	v_fmac_f32_e32 v62, v63, v62
	v_div_scale_f32 v63, vcc, 1.0, v60, 1.0
	v_mul_f32_e32 v67, v63, v62
	v_fma_f32 v92, -v61, v67, v63
	v_fmac_f32_e32 v67, v92, v62
	v_fma_f32 v61, -v61, v67, v63
	v_div_fmas_f32 v61, v61, v62, v67
	v_div_fixup_f32 v60, v61, v60, 1.0
	v_mul_f32_e32 v59, v59, v60
	v_mul_f32_e32 v60, 0xbfb8aa3b, v64
	v_exp_f32_e32 v60, v60
	s_nop 0
	v_add_f32_e32 v60, 1.0, v60
	v_div_scale_f32 v61, s[2:3], v60, v60, 1.0
	v_rcp_f32_e32 v62, v61
	s_nop 0
	v_fma_f32 v63, -v61, v62, 1.0
	v_fmac_f32_e32 v62, v63, v62
	v_div_scale_f32 v63, vcc, 1.0, v60, 1.0
	v_mul_f32_e32 v64, v63, v62
	v_fma_f32 v67, -v61, v64, v63
	v_fmac_f32_e32 v64, v67, v62
	v_fma_f32 v61, -v61, v64, v63
	v_div_fmas_f32 v61, v61, v62, v64
	v_div_fixup_f32 v60, v61, v60, 1.0
	v_mul_f32_e32 v60, v52, v60
	v_mul_f32_e32 v52, 0xbfb8aa3b, v65
	v_exp_f32_e32 v52, v52
	s_nop 0
	v_add_f32_e32 v52, 1.0, v52
	v_div_scale_f32 v61, s[2:3], v52, v52, 1.0
	v_rcp_f32_e32 v62, v61
	s_nop 0
	v_fma_f32 v63, -v61, v62, 1.0
	v_fmac_f32_e32 v62, v63, v62
	v_div_scale_f32 v63, vcc, 1.0, v52, 1.0
	v_mul_f32_e32 v64, v63, v62
	v_fma_f32 v65, -v61, v64, v63
	v_fmac_f32_e32 v64, v65, v62
	v_fma_f32 v61, -v61, v64, v63
	v_div_fmas_f32 v61, v61, v62, v64
	v_div_fixup_f32 v52, v61, v52, 1.0
	v_mul_f32_e32 v61, v53, v52
	v_mul_f32_e32 v52, 0xbfb8aa3b, v66
	v_exp_f32_e32 v52, v52
	s_nop 0
	v_add_f32_e32 v52, 1.0, v52
	v_div_scale_f32 v53, s[2:3], v52, v52, 1.0
	v_rcp_f32_e32 v62, v53
	s_nop 0
	v_fma_f32 v63, -v53, v62, 1.0
	v_fmac_f32_e32 v62, v63, v62
	v_div_scale_f32 v63, vcc, 1.0, v52, 1.0
	v_mul_f32_e32 v64, v63, v62
	v_fma_f32 v65, -v53, v64, v63
	v_fmac_f32_e32 v64, v65, v62
	v_fma_f32 v53, -v53, v64, v63
	v_div_fmas_f32 v53, v53, v62, v64
	v_div_fixup_f32 v52, v53, v52, 1.0
	v_mul_f32_e32 v62, v54, v52
	v_div_scale_f32 v52, s[2:3], v3, v3, 1.0
	v_rcp_f32_e32 v53, v52
	s_nop 0
	v_fma_f32 v54, -v52, v53, 1.0
	v_fmac_f32_e32 v53, v54, v53
	v_div_scale_f32 v54, vcc, 1.0, v3, 1.0
	v_mul_f32_e32 v63, v54, v53
	v_fma_f32 v64, -v52, v63, v54
	v_fmac_f32_e32 v63, v64, v53
	v_fma_f32 v52, -v52, v63, v54
	v_div_fmas_f32 v52, v52, v53, v63
	v_div_fixup_f32 v3, v52, v3, 1.0
	v_cvt_pk_bf16_f32 v52, v56, v57
	v_mul_f32_e32 v3, v55, v3
	v_cvt_pk_bf16_f32 v53, v58, v59
	v_cvt_pk_bf16_f32 v54, v60, v61
	v_cvt_pk_bf16_f32 v55, v62, v3
	buffer_store_dwordx4 v[52:55], v2, s[80:83], 0 offen offset:256 sc1
	v_lshlrev_b32_e32 v56, 16, v90
	v_and_b32_e32 v57, 0xffff0000, v90
	v_lshlrev_b32_e32 v52, 16, v88
	v_mul_f32_e32 v52, 0xbfb8aa3b, v52
	v_exp_f32_e32 v52, v52
	v_and_b32_e32 v53, 0xffff0000, v88
	v_lshlrev_b32_e32 v54, 16, v89
	v_and_b32_e32 v55, 0xffff0000, v89
	v_add_f32_e32 v52, 1.0, v52
	v_div_scale_f32 v59, s[2:3], v52, v52, 1.0
	v_rcp_f32_e32 v60, v59
	v_lshlrev_b32_e32 v58, 16, v91
	v_and_b32_e32 v3, 0xffff0000, v91
	v_mul_f32_e32 v3, 0xbfb8aa3b, v3
	v_fma_f32 v61, -v59, v60, 1.0
	v_fmac_f32_e32 v60, v61, v60
	v_div_scale_f32 v61, vcc, 1.0, v52, 1.0
	v_mul_f32_e32 v62, v61, v60
	v_fma_f32 v63, -v59, v62, v61
	v_fmac_f32_e32 v62, v63, v60
	v_fma_f32 v59, -v59, v62, v61
	v_div_fmas_f32 v59, v59, v60, v62
	v_div_fixup_f32 v52, v59, v52, 1.0
	v_mul_f32_e32 v48, v48, v52
	v_mul_f32_e32 v52, 0xbfb8aa3b, v53
	v_exp_f32_e32 v52, v52
	v_exp_f32_e32 v3, v3
	v_add_u32_e32 v2, 0x90000, v1
	v_add_f32_e32 v52, 1.0, v52
	v_div_scale_f32 v53, s[2:3], v52, v52, 1.0
	v_rcp_f32_e32 v59, v53
	v_add_f32_e32 v3, 1.0, v3
	v_fma_f32 v60, -v53, v59, 1.0
	v_fmac_f32_e32 v59, v60, v59
	v_div_scale_f32 v60, vcc, 1.0, v52, 1.0
	v_mul_f32_e32 v61, v60, v59
	v_fma_f32 v62, -v53, v61, v60
	v_fmac_f32_e32 v61, v62, v59
	v_fma_f32 v53, -v53, v61, v60
	v_div_fmas_f32 v53, v53, v59, v61
	v_div_fixup_f32 v52, v53, v52, 1.0
	v_mul_f32_e32 v49, v49, v52
	v_mul_f32_e32 v52, 0xbfb8aa3b, v54
	v_exp_f32_e32 v52, v52
	s_nop 0
	v_add_f32_e32 v52, 1.0, v52
	v_div_scale_f32 v53, s[2:3], v52, v52, 1.0
	v_rcp_f32_e32 v54, v53
	s_nop 0
	v_fma_f32 v59, -v53, v54, 1.0
	v_fmac_f32_e32 v54, v59, v54
	v_div_scale_f32 v59, vcc, 1.0, v52, 1.0
	v_mul_f32_e32 v60, v59, v54
	v_fma_f32 v61, -v53, v60, v59
	v_fmac_f32_e32 v60, v61, v54
	v_fma_f32 v53, -v53, v60, v59
	v_div_fmas_f32 v53, v53, v54, v60
	v_div_fixup_f32 v52, v53, v52, 1.0
	v_mul_f32_e32 v50, v50, v52
	v_mul_f32_e32 v52, 0xbfb8aa3b, v55
	v_exp_f32_e32 v52, v52
	s_nop 0
	v_add_f32_e32 v52, 1.0, v52
	v_div_scale_f32 v53, s[2:3], v52, v52, 1.0
	v_rcp_f32_e32 v54, v53
	s_nop 0
	v_fma_f32 v55, -v53, v54, 1.0
	v_fmac_f32_e32 v54, v55, v54
	v_div_scale_f32 v55, vcc, 1.0, v52, 1.0
	v_mul_f32_e32 v59, v55, v54
	v_fma_f32 v60, -v53, v59, v55
	v_fmac_f32_e32 v59, v60, v54
	v_fma_f32 v53, -v53, v59, v55
	v_div_fmas_f32 v53, v53, v54, v59
	v_div_fixup_f32 v52, v53, v52, 1.0
	v_mul_f32_e32 v51, v51, v52
	v_mul_f32_e32 v52, 0xbfb8aa3b, v56
	v_exp_f32_e32 v52, v52
	s_nop 0
	v_add_f32_e32 v52, 1.0, v52
	v_div_scale_f32 v53, s[2:3], v52, v52, 1.0
	v_rcp_f32_e32 v54, v53
	s_nop 0
	v_fma_f32 v55, -v53, v54, 1.0
	v_fmac_f32_e32 v54, v55, v54
	v_div_scale_f32 v55, vcc, 1.0, v52, 1.0
	v_mul_f32_e32 v56, v55, v54
	v_fma_f32 v59, -v53, v56, v55
	v_fmac_f32_e32 v56, v59, v54
	v_fma_f32 v53, -v53, v56, v55
	v_div_fmas_f32 v53, v53, v54, v56
	v_div_fixup_f32 v52, v53, v52, 1.0
	v_mul_f32_e32 v52, v44, v52
	v_mul_f32_e32 v44, 0xbfb8aa3b, v57
	v_exp_f32_e32 v44, v44
	s_nop 0
	v_add_f32_e32 v44, 1.0, v44
	v_div_scale_f32 v53, s[2:3], v44, v44, 1.0
	v_rcp_f32_e32 v54, v53
	s_nop 0
	v_fma_f32 v55, -v53, v54, 1.0
	v_fmac_f32_e32 v54, v55, v54
	v_div_scale_f32 v55, vcc, 1.0, v44, 1.0
	v_mul_f32_e32 v56, v55, v54
	v_fma_f32 v57, -v53, v56, v55
	v_fmac_f32_e32 v56, v57, v54
	v_fma_f32 v53, -v53, v56, v55
	v_div_fmas_f32 v53, v53, v54, v56
	v_div_fixup_f32 v44, v53, v44, 1.0
	v_mul_f32_e32 v53, v45, v44
	v_mul_f32_e32 v44, 0xbfb8aa3b, v58
	v_exp_f32_e32 v44, v44
	s_nop 0
	v_add_f32_e32 v44, 1.0, v44
	v_div_scale_f32 v45, s[2:3], v44, v44, 1.0
	v_rcp_f32_e32 v54, v45
	s_nop 0
	v_fma_f32 v55, -v45, v54, 1.0
	v_fmac_f32_e32 v54, v55, v54
	v_div_scale_f32 v55, vcc, 1.0, v44, 1.0
	v_mul_f32_e32 v56, v55, v54
	v_fma_f32 v57, -v45, v56, v55
	v_fmac_f32_e32 v56, v57, v54
	v_fma_f32 v45, -v45, v56, v55
	v_div_fmas_f32 v45, v45, v54, v56
	v_div_fixup_f32 v44, v45, v44, 1.0
	v_mul_f32_e32 v54, v46, v44
	v_div_scale_f32 v44, s[2:3], v3, v3, 1.0
	v_rcp_f32_e32 v45, v44
	s_nop 0
	v_fma_f32 v46, -v44, v45, 1.0
	v_fmac_f32_e32 v45, v46, v45
	v_div_scale_f32 v46, vcc, 1.0, v3, 1.0
	v_mul_f32_e32 v55, v46, v45
	v_fma_f32 v56, -v44, v55, v46
	v_fmac_f32_e32 v55, v56, v45
	v_fma_f32 v44, -v44, v55, v46
	v_div_fmas_f32 v44, v44, v45, v55
	v_div_fixup_f32 v3, v44, v3, 1.0
	v_cvt_pk_bf16_f32 v44, v48, v49
	v_mul_f32_e32 v3, v47, v3
	v_cvt_pk_bf16_f32 v45, v50, v51
	v_cvt_pk_bf16_f32 v46, v52, v53
	v_cvt_pk_bf16_f32 v47, v54, v3
	buffer_store_dwordx4 v[44:47], v2, s[80:83], 0 offen sc1
	v_lshlrev_b32_e32 v48, 16, v86
	v_and_b32_e32 v49, 0xffff0000, v86
	v_lshlrev_b32_e32 v44, 16, v84
	v_mul_f32_e32 v44, 0xbfb8aa3b, v44
	v_exp_f32_e32 v44, v44
	v_and_b32_e32 v45, 0xffff0000, v84
	v_lshlrev_b32_e32 v46, 16, v85
	v_and_b32_e32 v47, 0xffff0000, v85
	v_add_f32_e32 v44, 1.0, v44
	v_div_scale_f32 v51, s[2:3], v44, v44, 1.0
	v_rcp_f32_e32 v52, v51
	v_lshlrev_b32_e32 v50, 16, v87
	v_and_b32_e32 v3, 0xffff0000, v87
	v_mul_f32_e32 v3, 0xbfb8aa3b, v3
	v_fma_f32 v53, -v51, v52, 1.0
	v_fmac_f32_e32 v52, v53, v52
	v_div_scale_f32 v53, vcc, 1.0, v44, 1.0
	v_mul_f32_e32 v54, v53, v52
	v_fma_f32 v55, -v51, v54, v53
	v_fmac_f32_e32 v54, v55, v52
	v_fma_f32 v51, -v51, v54, v53
	v_div_fmas_f32 v51, v51, v52, v54
	v_div_fixup_f32 v44, v51, v44, 1.0
	v_mul_f32_e32 v40, v40, v44
	v_mul_f32_e32 v44, 0xbfb8aa3b, v45
	v_exp_f32_e32 v44, v44
	v_exp_f32_e32 v3, v3
	v_add_f32_e32 v44, 1.0, v44
	v_div_scale_f32 v45, s[2:3], v44, v44, 1.0
	v_rcp_f32_e32 v51, v45
	v_add_f32_e32 v3, 1.0, v3
	v_fma_f32 v52, -v45, v51, 1.0
	v_fmac_f32_e32 v51, v52, v51
	v_div_scale_f32 v52, vcc, 1.0, v44, 1.0
	v_mul_f32_e32 v53, v52, v51
	v_fma_f32 v54, -v45, v53, v52
	v_fmac_f32_e32 v53, v54, v51
	v_fma_f32 v45, -v45, v53, v52
	v_div_fmas_f32 v45, v45, v51, v53
	v_div_fixup_f32 v44, v45, v44, 1.0
	v_mul_f32_e32 v41, v41, v44
	v_mul_f32_e32 v44, 0xbfb8aa3b, v46
	v_exp_f32_e32 v44, v44
	s_nop 0
	v_add_f32_e32 v44, 1.0, v44
	v_div_scale_f32 v45, s[2:3], v44, v44, 1.0
	v_rcp_f32_e32 v46, v45
	s_nop 0
	v_fma_f32 v51, -v45, v46, 1.0
	v_fmac_f32_e32 v46, v51, v46
	v_div_scale_f32 v51, vcc, 1.0, v44, 1.0
	v_mul_f32_e32 v52, v51, v46
	v_fma_f32 v53, -v45, v52, v51
	v_fmac_f32_e32 v52, v53, v46
	v_fma_f32 v45, -v45, v52, v51
	v_div_fmas_f32 v45, v45, v46, v52
	v_div_fixup_f32 v44, v45, v44, 1.0
	v_mul_f32_e32 v42, v42, v44
	v_mul_f32_e32 v44, 0xbfb8aa3b, v47
	v_exp_f32_e32 v44, v44
	s_nop 0
	v_add_f32_e32 v44, 1.0, v44
	v_div_scale_f32 v45, s[2:3], v44, v44, 1.0
	v_rcp_f32_e32 v46, v45
	s_nop 0
	v_fma_f32 v47, -v45, v46, 1.0
	v_fmac_f32_e32 v46, v47, v46
	v_div_scale_f32 v47, vcc, 1.0, v44, 1.0
	v_mul_f32_e32 v51, v47, v46
	v_fma_f32 v52, -v45, v51, v47
	v_fmac_f32_e32 v51, v52, v46
	v_fma_f32 v45, -v45, v51, v47
	v_div_fmas_f32 v45, v45, v46, v51
	v_div_fixup_f32 v44, v45, v44, 1.0
	v_mul_f32_e32 v43, v43, v44
	v_mul_f32_e32 v44, 0xbfb8aa3b, v48
	v_exp_f32_e32 v44, v44
	s_nop 0
	v_add_f32_e32 v44, 1.0, v44
	v_div_scale_f32 v45, s[2:3], v44, v44, 1.0
	v_rcp_f32_e32 v46, v45
	s_nop 0
	v_fma_f32 v47, -v45, v46, 1.0
	v_fmac_f32_e32 v46, v47, v46
	v_div_scale_f32 v47, vcc, 1.0, v44, 1.0
	v_mul_f32_e32 v48, v47, v46
	v_fma_f32 v51, -v45, v48, v47
	v_fmac_f32_e32 v48, v51, v46
	v_fma_f32 v45, -v45, v48, v47
	v_div_fmas_f32 v45, v45, v46, v48
	v_div_fixup_f32 v44, v45, v44, 1.0
	v_mul_f32_e32 v44, v36, v44
	v_mul_f32_e32 v36, 0xbfb8aa3b, v49
	v_exp_f32_e32 v36, v36
	s_nop 0
	v_add_f32_e32 v36, 1.0, v36
	v_div_scale_f32 v45, s[2:3], v36, v36, 1.0
	v_rcp_f32_e32 v46, v45
	s_nop 0
	v_fma_f32 v47, -v45, v46, 1.0
	v_fmac_f32_e32 v46, v47, v46
	v_div_scale_f32 v47, vcc, 1.0, v36, 1.0
	v_mul_f32_e32 v48, v47, v46
	v_fma_f32 v49, -v45, v48, v47
	v_fmac_f32_e32 v48, v49, v46
	v_fma_f32 v45, -v45, v48, v47
	v_div_fmas_f32 v45, v45, v46, v48
	v_div_fixup_f32 v36, v45, v36, 1.0
	v_mul_f32_e32 v45, v37, v36
	v_mul_f32_e32 v36, 0xbfb8aa3b, v50
	v_exp_f32_e32 v36, v36
	s_nop 0
	v_add_f32_e32 v36, 1.0, v36
	v_div_scale_f32 v37, s[2:3], v36, v36, 1.0
	v_rcp_f32_e32 v46, v37
	s_nop 0
	v_fma_f32 v47, -v37, v46, 1.0
	v_fmac_f32_e32 v46, v47, v46
	v_div_scale_f32 v47, vcc, 1.0, v36, 1.0
	v_mul_f32_e32 v48, v47, v46
	v_fma_f32 v49, -v37, v48, v47
	v_fmac_f32_e32 v48, v49, v46
	v_fma_f32 v37, -v37, v48, v47
	v_div_fmas_f32 v37, v37, v46, v48
	v_div_fixup_f32 v36, v37, v36, 1.0
	v_mul_f32_e32 v46, v38, v36
	v_div_scale_f32 v36, s[2:3], v3, v3, 1.0
	v_rcp_f32_e32 v37, v36
	s_nop 0
	v_fma_f32 v38, -v36, v37, 1.0
	v_fmac_f32_e32 v37, v38, v37
	v_div_scale_f32 v38, vcc, 1.0, v3, 1.0
	v_mul_f32_e32 v47, v38, v37
	v_fma_f32 v48, -v36, v47, v38
	v_fmac_f32_e32 v47, v48, v37
	v_fma_f32 v36, -v36, v47, v38
	v_div_fmas_f32 v36, v36, v37, v47
	v_div_fixup_f32 v3, v36, v3, 1.0
	v_cvt_pk_bf16_f32 v36, v40, v41
	v_mul_f32_e32 v3, v39, v3
	v_cvt_pk_bf16_f32 v37, v42, v43
	v_cvt_pk_bf16_f32 v38, v44, v45
	v_cvt_pk_bf16_f32 v39, v46, v3
	buffer_store_dwordx4 v[36:39], v2, s[80:83], 0 offen offset:256 sc1
	v_lshlrev_b32_e32 v40, 16, v82
	v_and_b32_e32 v41, 0xffff0000, v82
	v_lshlrev_b32_e32 v36, 16, v80
	v_mul_f32_e32 v36, 0xbfb8aa3b, v36
	v_exp_f32_e32 v36, v36
	v_and_b32_e32 v37, 0xffff0000, v80
	v_lshlrev_b32_e32 v38, 16, v81
	v_and_b32_e32 v39, 0xffff0000, v81
	v_add_f32_e32 v36, 1.0, v36
	v_div_scale_f32 v43, s[2:3], v36, v36, 1.0
	v_rcp_f32_e32 v44, v43
	v_lshlrev_b32_e32 v42, 16, v83
	v_and_b32_e32 v3, 0xffff0000, v83
	v_mul_f32_e32 v3, 0xbfb8aa3b, v3
	v_fma_f32 v45, -v43, v44, 1.0
	v_fmac_f32_e32 v44, v45, v44
	v_div_scale_f32 v45, vcc, 1.0, v36, 1.0
	v_mul_f32_e32 v46, v45, v44
	v_fma_f32 v47, -v43, v46, v45
	v_fmac_f32_e32 v46, v47, v44
	v_fma_f32 v43, -v43, v46, v45
	v_div_fmas_f32 v43, v43, v44, v46
	v_div_fixup_f32 v36, v43, v36, 1.0
	v_mul_f32_e32 v32, v32, v36
	v_mul_f32_e32 v36, 0xbfb8aa3b, v37
	v_exp_f32_e32 v36, v36
	v_exp_f32_e32 v3, v3
	v_add_u32_e32 v2, 0xa0000, v1
	v_add_u32_e32 v1, 0xb0000, v1
	v_add_f32_e32 v36, 1.0, v36
	v_div_scale_f32 v37, s[2:3], v36, v36, 1.0
	v_rcp_f32_e32 v43, v37
	v_add_f32_e32 v3, 1.0, v3
	v_fma_f32 v44, -v37, v43, 1.0
	v_fmac_f32_e32 v43, v44, v43
	v_div_scale_f32 v44, vcc, 1.0, v36, 1.0
	v_mul_f32_e32 v45, v44, v43
	v_fma_f32 v46, -v37, v45, v44
	v_fmac_f32_e32 v45, v46, v43
	v_fma_f32 v37, -v37, v45, v44
	v_div_fmas_f32 v37, v37, v43, v45
	v_div_fixup_f32 v36, v37, v36, 1.0
	v_mul_f32_e32 v33, v33, v36
	v_mul_f32_e32 v36, 0xbfb8aa3b, v38
	v_exp_f32_e32 v36, v36
	s_nop 0
	v_add_f32_e32 v36, 1.0, v36
	v_div_scale_f32 v37, s[2:3], v36, v36, 1.0
	v_rcp_f32_e32 v38, v37
	s_nop 0
	v_fma_f32 v43, -v37, v38, 1.0
	v_fmac_f32_e32 v38, v43, v38
	v_div_scale_f32 v43, vcc, 1.0, v36, 1.0
	v_mul_f32_e32 v44, v43, v38
	v_fma_f32 v45, -v37, v44, v43
	v_fmac_f32_e32 v44, v45, v38
	v_fma_f32 v37, -v37, v44, v43
	v_div_fmas_f32 v37, v37, v38, v44
	v_div_fixup_f32 v36, v37, v36, 1.0
	v_mul_f32_e32 v34, v34, v36
	v_mul_f32_e32 v36, 0xbfb8aa3b, v39
	v_exp_f32_e32 v36, v36
	s_nop 0
	v_add_f32_e32 v36, 1.0, v36
	v_div_scale_f32 v37, s[2:3], v36, v36, 1.0
	v_rcp_f32_e32 v38, v37
	s_nop 0
	v_fma_f32 v39, -v37, v38, 1.0
	v_fmac_f32_e32 v38, v39, v38
	v_div_scale_f32 v39, vcc, 1.0, v36, 1.0
	v_mul_f32_e32 v43, v39, v38
	v_fma_f32 v44, -v37, v43, v39
	v_fmac_f32_e32 v43, v44, v38
	v_fma_f32 v37, -v37, v43, v39
	v_div_fmas_f32 v37, v37, v38, v43
	v_div_fixup_f32 v36, v37, v36, 1.0
	v_mul_f32_e32 v35, v35, v36
	v_mul_f32_e32 v36, 0xbfb8aa3b, v40
	v_exp_f32_e32 v36, v36
	s_nop 0
	v_add_f32_e32 v36, 1.0, v36
	v_div_scale_f32 v37, s[2:3], v36, v36, 1.0
	v_rcp_f32_e32 v38, v37
	s_nop 0
	v_fma_f32 v39, -v37, v38, 1.0
	v_fmac_f32_e32 v38, v39, v38
	v_div_scale_f32 v39, vcc, 1.0, v36, 1.0
	v_mul_f32_e32 v40, v39, v38
	v_fma_f32 v43, -v37, v40, v39
	v_fmac_f32_e32 v40, v43, v38
	v_fma_f32 v37, -v37, v40, v39
	v_div_fmas_f32 v37, v37, v38, v40
	v_div_fixup_f32 v36, v37, v36, 1.0
	v_mul_f32_e32 v36, v28, v36
	v_mul_f32_e32 v28, 0xbfb8aa3b, v41
	v_exp_f32_e32 v28, v28
	s_nop 0
	v_add_f32_e32 v28, 1.0, v28
	v_div_scale_f32 v37, s[2:3], v28, v28, 1.0
	v_rcp_f32_e32 v38, v37
	s_nop 0
	v_fma_f32 v39, -v37, v38, 1.0
	v_fmac_f32_e32 v38, v39, v38
	v_div_scale_f32 v39, vcc, 1.0, v28, 1.0
	v_mul_f32_e32 v40, v39, v38
	v_fma_f32 v41, -v37, v40, v39
	v_fmac_f32_e32 v40, v41, v38
	v_fma_f32 v37, -v37, v40, v39
	v_div_fmas_f32 v37, v37, v38, v40
	v_div_fixup_f32 v28, v37, v28, 1.0
	v_mul_f32_e32 v37, v29, v28
	v_mul_f32_e32 v28, 0xbfb8aa3b, v42
	v_exp_f32_e32 v28, v28
	s_nop 0
	v_add_f32_e32 v28, 1.0, v28
	v_div_scale_f32 v29, s[2:3], v28, v28, 1.0
	v_rcp_f32_e32 v38, v29
	s_nop 0
	v_fma_f32 v39, -v29, v38, 1.0
	v_fmac_f32_e32 v38, v39, v38
	v_div_scale_f32 v39, vcc, 1.0, v28, 1.0
	v_mul_f32_e32 v40, v39, v38
	v_fma_f32 v41, -v29, v40, v39
	v_fmac_f32_e32 v40, v41, v38
	v_fma_f32 v29, -v29, v40, v39
	v_div_fmas_f32 v29, v29, v38, v40
	v_div_fixup_f32 v28, v29, v28, 1.0
	v_mul_f32_e32 v38, v30, v28
	v_div_scale_f32 v28, s[2:3], v3, v3, 1.0
	v_rcp_f32_e32 v29, v28
	s_nop 0
	v_fma_f32 v30, -v28, v29, 1.0
	v_fmac_f32_e32 v29, v30, v29
	v_div_scale_f32 v30, vcc, 1.0, v3, 1.0
	v_mul_f32_e32 v39, v30, v29
	v_fma_f32 v40, -v28, v39, v30
	v_fmac_f32_e32 v39, v40, v29
	v_fma_f32 v28, -v28, v39, v30
	v_div_fmas_f32 v28, v28, v29, v39
	v_div_fixup_f32 v3, v28, v3, 1.0
	v_cvt_pk_bf16_f32 v28, v32, v33
	v_mul_f32_e32 v3, v31, v3
	v_cvt_pk_bf16_f32 v29, v34, v35
	v_cvt_pk_bf16_f32 v30, v36, v37
	v_cvt_pk_bf16_f32 v31, v38, v3
	buffer_store_dwordx4 v[28:31], v2, s[80:83], 0 offen sc1
	v_lshlrev_b32_e32 v32, 16, v78
	v_and_b32_e32 v33, 0xffff0000, v78
	v_lshlrev_b32_e32 v28, 16, v76
	v_mul_f32_e32 v28, 0xbfb8aa3b, v28
	v_exp_f32_e32 v28, v28
	v_and_b32_e32 v29, 0xffff0000, v76
	v_lshlrev_b32_e32 v30, 16, v77
	v_and_b32_e32 v31, 0xffff0000, v77
	v_add_f32_e32 v28, 1.0, v28
	v_div_scale_f32 v35, s[2:3], v28, v28, 1.0
	v_rcp_f32_e32 v36, v35
	v_lshlrev_b32_e32 v34, 16, v79
	v_and_b32_e32 v3, 0xffff0000, v79
	v_mul_f32_e32 v3, 0xbfb8aa3b, v3
	v_fma_f32 v37, -v35, v36, 1.0
	v_fmac_f32_e32 v36, v37, v36
	v_div_scale_f32 v37, vcc, 1.0, v28, 1.0
	v_mul_f32_e32 v38, v37, v36
	v_fma_f32 v39, -v35, v38, v37
	v_fmac_f32_e32 v38, v39, v36
	v_fma_f32 v35, -v35, v38, v37
	v_div_fmas_f32 v35, v35, v36, v38
	v_div_fixup_f32 v28, v35, v28, 1.0
	v_mul_f32_e32 v24, v24, v28
	v_mul_f32_e32 v28, 0xbfb8aa3b, v29
	v_exp_f32_e32 v28, v28
	v_exp_f32_e32 v3, v3
	v_add_f32_e32 v28, 1.0, v28
	v_div_scale_f32 v29, s[2:3], v28, v28, 1.0
	v_rcp_f32_e32 v35, v29
	v_add_f32_e32 v3, 1.0, v3
	v_fma_f32 v36, -v29, v35, 1.0
	v_fmac_f32_e32 v35, v36, v35
	v_div_scale_f32 v36, vcc, 1.0, v28, 1.0
	v_mul_f32_e32 v37, v36, v35
	v_fma_f32 v38, -v29, v37, v36
	v_fmac_f32_e32 v37, v38, v35
	v_fma_f32 v29, -v29, v37, v36
	v_div_fmas_f32 v29, v29, v35, v37
	v_div_fixup_f32 v28, v29, v28, 1.0
	v_mul_f32_e32 v25, v25, v28
	v_mul_f32_e32 v28, 0xbfb8aa3b, v30
	v_exp_f32_e32 v28, v28
	s_nop 0
	v_add_f32_e32 v28, 1.0, v28
	v_div_scale_f32 v29, s[2:3], v28, v28, 1.0
	v_rcp_f32_e32 v30, v29
	s_nop 0
	v_fma_f32 v35, -v29, v30, 1.0
	v_fmac_f32_e32 v30, v35, v30
	v_div_scale_f32 v35, vcc, 1.0, v28, 1.0
	v_mul_f32_e32 v36, v35, v30
	v_fma_f32 v37, -v29, v36, v35
	v_fmac_f32_e32 v36, v37, v30
	v_fma_f32 v29, -v29, v36, v35
	v_div_fmas_f32 v29, v29, v30, v36
	v_div_fixup_f32 v28, v29, v28, 1.0
	v_mul_f32_e32 v26, v26, v28
	v_mul_f32_e32 v28, 0xbfb8aa3b, v31
	v_exp_f32_e32 v28, v28
	s_nop 0
	v_add_f32_e32 v28, 1.0, v28
	v_div_scale_f32 v29, s[2:3], v28, v28, 1.0
	v_rcp_f32_e32 v30, v29
	s_nop 0
	v_fma_f32 v31, -v29, v30, 1.0
	v_fmac_f32_e32 v30, v31, v30
	v_div_scale_f32 v31, vcc, 1.0, v28, 1.0
	v_mul_f32_e32 v35, v31, v30
	v_fma_f32 v36, -v29, v35, v31
	v_fmac_f32_e32 v35, v36, v30
	v_fma_f32 v29, -v29, v35, v31
	v_div_fmas_f32 v29, v29, v30, v35
	v_div_fixup_f32 v28, v29, v28, 1.0
	v_mul_f32_e32 v27, v27, v28
	v_mul_f32_e32 v28, 0xbfb8aa3b, v32
	v_exp_f32_e32 v28, v28
	s_nop 0
	v_add_f32_e32 v28, 1.0, v28
	v_div_scale_f32 v29, s[2:3], v28, v28, 1.0
	v_rcp_f32_e32 v30, v29
	s_nop 0
	v_fma_f32 v31, -v29, v30, 1.0
	v_fmac_f32_e32 v30, v31, v30
	v_div_scale_f32 v31, vcc, 1.0, v28, 1.0
	v_mul_f32_e32 v32, v31, v30
	v_fma_f32 v35, -v29, v32, v31
	v_fmac_f32_e32 v32, v35, v30
	v_fma_f32 v29, -v29, v32, v31
	v_div_fmas_f32 v29, v29, v30, v32
	v_div_fixup_f32 v28, v29, v28, 1.0
	v_mul_f32_e32 v28, v20, v28
	v_mul_f32_e32 v20, 0xbfb8aa3b, v33
	v_exp_f32_e32 v20, v20
	s_nop 0
	v_add_f32_e32 v20, 1.0, v20
	v_div_scale_f32 v29, s[2:3], v20, v20, 1.0
	v_rcp_f32_e32 v30, v29
	s_nop 0
	v_fma_f32 v31, -v29, v30, 1.0
	v_fmac_f32_e32 v30, v31, v30
	v_div_scale_f32 v31, vcc, 1.0, v20, 1.0
	v_mul_f32_e32 v32, v31, v30
	v_fma_f32 v33, -v29, v32, v31
	v_fmac_f32_e32 v32, v33, v30
	v_fma_f32 v29, -v29, v32, v31
	v_div_fmas_f32 v29, v29, v30, v32
	v_div_fixup_f32 v20, v29, v20, 1.0
	v_mul_f32_e32 v29, v21, v20
	v_mul_f32_e32 v20, 0xbfb8aa3b, v34
	v_exp_f32_e32 v20, v20
	s_nop 0
	v_add_f32_e32 v20, 1.0, v20
	v_div_scale_f32 v21, s[2:3], v20, v20, 1.0
	v_rcp_f32_e32 v30, v21
	s_nop 0
	v_fma_f32 v31, -v21, v30, 1.0
	v_fmac_f32_e32 v30, v31, v30
	v_div_scale_f32 v31, vcc, 1.0, v20, 1.0
	v_mul_f32_e32 v32, v31, v30
	v_fma_f32 v33, -v21, v32, v31
	v_fmac_f32_e32 v32, v33, v30
	v_fma_f32 v21, -v21, v32, v31
	v_div_fmas_f32 v21, v21, v30, v32
	v_div_fixup_f32 v20, v21, v20, 1.0
	v_mul_f32_e32 v30, v22, v20
	v_div_scale_f32 v20, s[2:3], v3, v3, 1.0
	v_rcp_f32_e32 v21, v20
	s_nop 0
	v_fma_f32 v22, -v20, v21, 1.0
	v_fmac_f32_e32 v21, v22, v21
	v_div_scale_f32 v22, vcc, 1.0, v3, 1.0
	v_mul_f32_e32 v31, v22, v21
	v_fma_f32 v32, -v20, v31, v22
	v_fmac_f32_e32 v31, v32, v21
	v_fma_f32 v20, -v20, v31, v22
	v_div_fmas_f32 v20, v20, v21, v31
	v_div_fixup_f32 v3, v20, v3, 1.0
	v_mul_f32_e32 v3, v23, v3
	v_cvt_pk_bf16_f32 v20, v24, v25
	v_cvt_pk_bf16_f32 v21, v26, v27
	v_cvt_pk_bf16_f32 v22, v28, v29
	v_cvt_pk_bf16_f32 v23, v30, v3
	v_lshlrev_b32_e32 v3, 16, v72
	v_mul_f32_e32 v3, 0xbfb8aa3b, v3
	v_exp_f32_e32 v3, v3
	buffer_store_dwordx4 v[20:23], v2, s[80:83], 0 offen offset:256 sc1
	v_and_b32_e32 v24, 0xffff0000, v74
	v_lshlrev_b32_e32 v25, 16, v75
	v_add_f32_e32 v3, 1.0, v3
	v_div_scale_f32 v26, s[2:3], v3, v3, 1.0
	v_rcp_f32_e32 v27, v26
	v_and_b32_e32 v20, 0xffff0000, v72
	v_lshlrev_b32_e32 v21, 16, v73
	v_and_b32_e32 v22, 0xffff0000, v73
	v_fma_f32 v28, -v26, v27, 1.0
	v_fmac_f32_e32 v27, v28, v27
	v_div_scale_f32 v28, vcc, 1.0, v3, 1.0
	v_mul_f32_e32 v29, v28, v27
	v_fma_f32 v30, -v26, v29, v28
	v_fmac_f32_e32 v29, v30, v27
	v_fma_f32 v26, -v26, v29, v28
	v_div_fmas_f32 v26, v26, v27, v29
	v_div_fixup_f32 v3, v26, v3, 1.0
	v_mul_f32_e32 v3, v16, v3
	v_mul_f32_e32 v16, 0xbfb8aa3b, v20
	v_exp_f32_e32 v16, v16
	v_lshlrev_b32_e32 v23, 16, v74
	v_and_b32_e32 v2, 0xffff0000, v75
	v_mul_f32_e32 v2, 0xbfb8aa3b, v2
	v_add_f32_e32 v16, 1.0, v16
	v_div_scale_f32 v20, s[2:3], v16, v16, 1.0
	v_rcp_f32_e32 v26, v20
	v_exp_f32_e32 v2, v2
	v_fma_f32 v27, -v20, v26, 1.0
	v_fmac_f32_e32 v26, v27, v26
	v_div_scale_f32 v27, vcc, 1.0, v16, 1.0
	v_mul_f32_e32 v28, v27, v26
	v_fma_f32 v29, -v20, v28, v27
	v_fmac_f32_e32 v28, v29, v26
	v_fma_f32 v20, -v20, v28, v27
	v_div_fmas_f32 v20, v20, v26, v28
	v_div_fixup_f32 v16, v20, v16, 1.0
	v_mul_f32_e32 v16, v17, v16
	v_mul_f32_e32 v17, 0xbfb8aa3b, v21
	v_exp_f32_e32 v17, v17
	v_add_f32_e32 v2, 1.0, v2
	v_add_f32_e32 v17, 1.0, v17
	v_div_scale_f32 v20, s[2:3], v17, v17, 1.0
	v_rcp_f32_e32 v21, v20
	s_nop 0
	v_fma_f32 v26, -v20, v21, 1.0
	v_fmac_f32_e32 v21, v26, v21
	v_div_scale_f32 v26, vcc, 1.0, v17, 1.0
	v_mul_f32_e32 v27, v26, v21
	v_fma_f32 v28, -v20, v27, v26
	v_fmac_f32_e32 v27, v28, v21
	v_fma_f32 v20, -v20, v27, v26
	v_div_fmas_f32 v20, v20, v21, v27
	v_div_fixup_f32 v17, v20, v17, 1.0
	v_mul_f32_e32 v17, v18, v17
	v_mul_f32_e32 v18, 0xbfb8aa3b, v22
	v_exp_f32_e32 v18, v18
	s_nop 0
	v_add_f32_e32 v18, 1.0, v18
	v_div_scale_f32 v20, s[2:3], v18, v18, 1.0
	v_rcp_f32_e32 v21, v20
	s_nop 0
	v_fma_f32 v22, -v20, v21, 1.0
	v_fmac_f32_e32 v21, v22, v21
	v_div_scale_f32 v22, vcc, 1.0, v18, 1.0
	v_mul_f32_e32 v26, v22, v21
	v_fma_f32 v27, -v20, v26, v22
	v_fmac_f32_e32 v26, v27, v21
	v_fma_f32 v20, -v20, v26, v22
	v_div_fmas_f32 v20, v20, v21, v26
	v_div_fixup_f32 v18, v20, v18, 1.0
	v_mul_f32_e32 v18, v19, v18
	v_mul_f32_e32 v19, 0xbfb8aa3b, v23
	v_exp_f32_e32 v19, v19
	s_nop 0
	v_add_f32_e32 v19, 1.0, v19
	v_div_scale_f32 v20, s[2:3], v19, v19, 1.0
	v_rcp_f32_e32 v21, v20
	s_nop 0
	v_fma_f32 v22, -v20, v21, 1.0
	v_fmac_f32_e32 v21, v22, v21
	v_div_scale_f32 v22, vcc, 1.0, v19, 1.0
	v_mul_f32_e32 v23, v22, v21
	v_fma_f32 v26, -v20, v23, v22
	v_fmac_f32_e32 v23, v26, v21
	v_fma_f32 v20, -v20, v23, v22
	v_div_fmas_f32 v20, v20, v21, v23
	v_div_fixup_f32 v19, v20, v19, 1.0
	v_mul_f32_e32 v19, v12, v19
	v_mul_f32_e32 v12, 0xbfb8aa3b, v24
	v_exp_f32_e32 v12, v12
	s_nop 0
	v_add_f32_e32 v12, 1.0, v12
	v_div_scale_f32 v20, s[2:3], v12, v12, 1.0
	v_rcp_f32_e32 v21, v20
	s_nop 0
	v_fma_f32 v22, -v20, v21, 1.0
	v_fmac_f32_e32 v21, v22, v21
	v_div_scale_f32 v22, vcc, 1.0, v12, 1.0
	v_mul_f32_e32 v23, v22, v21
	v_fma_f32 v24, -v20, v23, v22
	v_fmac_f32_e32 v23, v24, v21
	v_fma_f32 v20, -v20, v23, v22
	v_div_fmas_f32 v20, v20, v21, v23
	v_div_fixup_f32 v12, v20, v12, 1.0
	v_mul_f32_e32 v20, v13, v12
	v_mul_f32_e32 v12, 0xbfb8aa3b, v25
	v_exp_f32_e32 v12, v12
	s_nop 0
	v_add_f32_e32 v12, 1.0, v12
	v_div_scale_f32 v13, s[2:3], v12, v12, 1.0
	v_rcp_f32_e32 v21, v13
	s_nop 0
	v_fma_f32 v22, -v13, v21, 1.0
	v_fmac_f32_e32 v21, v22, v21
	v_div_scale_f32 v22, vcc, 1.0, v12, 1.0
	v_mul_f32_e32 v23, v22, v21
	v_fma_f32 v24, -v13, v23, v22
	v_fmac_f32_e32 v23, v24, v21
	v_fma_f32 v13, -v13, v23, v22
	v_div_fmas_f32 v13, v13, v21, v23
	v_div_fixup_f32 v12, v13, v12, 1.0
	v_mul_f32_e32 v21, v14, v12
	v_div_scale_f32 v12, s[2:3], v2, v2, 1.0
	v_rcp_f32_e32 v13, v12
	s_nop 0
	v_fma_f32 v14, -v12, v13, 1.0
	v_fmac_f32_e32 v13, v14, v13
	v_div_scale_f32 v14, vcc, 1.0, v2, 1.0
	v_mul_f32_e32 v22, v14, v13
	v_fma_f32 v23, -v12, v22, v14
	v_fmac_f32_e32 v22, v23, v13
	v_fma_f32 v12, -v12, v22, v14
	v_div_fmas_f32 v12, v12, v13, v22
	v_div_fixup_f32 v2, v12, v2, 1.0
	v_cvt_pk_bf16_f32 v12, v3, v16
	s_waitcnt vmcnt(6)
	v_lshlrev_b32_e32 v3, 16, v68
	v_mul_f32_e32 v3, 0xbfb8aa3b, v3
	v_exp_f32_e32 v3, v3
	v_cvt_pk_bf16_f32 v13, v17, v18
	v_cvt_pk_bf16_f32 v14, v19, v20
	v_mul_f32_e32 v2, v15, v2
	v_add_f32_e32 v3, 1.0, v3
	v_div_scale_f32 v18, s[2:3], v3, v3, 1.0
	v_rcp_f32_e32 v19, v18
	v_cvt_pk_bf16_f32 v15, v21, v2
	buffer_store_dwordx4 v[12:15], v1, s[80:83], 0 offen sc1
	v_and_b32_e32 v16, 0xffff0000, v70
	v_fma_f32 v20, -v18, v19, 1.0
	v_fmac_f32_e32 v19, v20, v19
	v_div_scale_f32 v20, vcc, 1.0, v3, 1.0
	v_mul_f32_e32 v21, v20, v19
	v_fma_f32 v22, -v18, v21, v20
	v_fmac_f32_e32 v21, v22, v19
	v_fma_f32 v18, -v18, v21, v20
	v_div_fmas_f32 v18, v18, v19, v21
	v_and_b32_e32 v12, 0xffff0000, v68
	v_div_fixup_f32 v3, v18, v3, 1.0
	v_mul_f32_e32 v3, v8, v3
	v_mul_f32_e32 v8, 0xbfb8aa3b, v12
	v_exp_f32_e32 v8, v8
	v_lshlrev_b32_e32 v13, 16, v69
	v_and_b32_e32 v14, 0xffff0000, v69
	v_lshlrev_b32_e32 v15, 16, v70
	v_add_f32_e32 v8, 1.0, v8
	v_div_scale_f32 v12, s[2:3], v8, v8, 1.0
	v_rcp_f32_e32 v18, v12
	v_lshlrev_b32_e32 v17, 16, v71
	v_and_b32_e32 v2, 0xffff0000, v71
	v_mul_f32_e32 v2, 0xbfb8aa3b, v2
	v_fma_f32 v19, -v12, v18, 1.0
	v_fmac_f32_e32 v18, v19, v18
	v_div_scale_f32 v19, vcc, 1.0, v8, 1.0
	v_mul_f32_e32 v20, v19, v18
	v_fma_f32 v21, -v12, v20, v19
	v_fmac_f32_e32 v20, v21, v18
	v_fma_f32 v12, -v12, v20, v19
	v_div_fmas_f32 v12, v12, v18, v20
	v_div_fixup_f32 v8, v12, v8, 1.0
	v_mul_f32_e32 v8, v9, v8
	v_mul_f32_e32 v9, 0xbfb8aa3b, v13
	v_exp_f32_e32 v9, v9
	v_exp_f32_e32 v2, v2
	v_add_f32_e32 v9, 1.0, v9
	v_div_scale_f32 v12, s[2:3], v9, v9, 1.0
	v_rcp_f32_e32 v13, v12
	v_add_f32_e32 v2, 1.0, v2
	v_fma_f32 v18, -v12, v13, 1.0
	v_fmac_f32_e32 v13, v18, v13
	v_div_scale_f32 v18, vcc, 1.0, v9, 1.0
	v_mul_f32_e32 v19, v18, v13
	v_fma_f32 v20, -v12, v19, v18
	v_fmac_f32_e32 v19, v20, v13
	v_fma_f32 v12, -v12, v19, v18
	v_div_fmas_f32 v12, v12, v13, v19
	v_div_fixup_f32 v9, v12, v9, 1.0
	v_mul_f32_e32 v9, v10, v9
	v_mul_f32_e32 v10, 0xbfb8aa3b, v14
	v_exp_f32_e32 v10, v10
	s_nop 0
	v_add_f32_e32 v10, 1.0, v10
	v_div_scale_f32 v12, s[2:3], v10, v10, 1.0
	v_rcp_f32_e32 v13, v12
	s_nop 0
	v_fma_f32 v14, -v12, v13, 1.0
	v_fmac_f32_e32 v13, v14, v13
	v_div_scale_f32 v14, vcc, 1.0, v10, 1.0
	v_mul_f32_e32 v18, v14, v13
	v_fma_f32 v19, -v12, v18, v14
	v_fmac_f32_e32 v18, v19, v13
	v_fma_f32 v12, -v12, v18, v14
	v_div_fmas_f32 v12, v12, v13, v18
	v_div_fixup_f32 v10, v12, v10, 1.0
	v_mul_f32_e32 v10, v11, v10
	v_mul_f32_e32 v11, 0xbfb8aa3b, v15
	v_exp_f32_e32 v11, v11
	s_nop 0
	v_add_f32_e32 v11, 1.0, v11
	v_div_scale_f32 v12, s[2:3], v11, v11, 1.0
	v_rcp_f32_e32 v13, v12
	s_nop 0
	v_fma_f32 v14, -v12, v13, 1.0
	v_fmac_f32_e32 v13, v14, v13
	v_div_scale_f32 v14, vcc, 1.0, v11, 1.0
	v_mul_f32_e32 v15, v14, v13
	v_fma_f32 v18, -v12, v15, v14
	v_fmac_f32_e32 v15, v18, v13
	v_fma_f32 v12, -v12, v15, v14
	v_div_fmas_f32 v12, v12, v13, v15
	v_div_fixup_f32 v11, v12, v11, 1.0
	v_mul_f32_e32 v4, v4, v11
	v_mul_f32_e32 v11, 0xbfb8aa3b, v16
	v_exp_f32_e32 v11, v11
	s_nop 0
	v_add_f32_e32 v11, 1.0, v11
	v_div_scale_f32 v12, s[2:3], v11, v11, 1.0
	v_rcp_f32_e32 v13, v12
	s_nop 0
	v_fma_f32 v14, -v12, v13, 1.0
	v_fmac_f32_e32 v13, v14, v13
	v_div_scale_f32 v14, vcc, 1.0, v11, 1.0
	v_mul_f32_e32 v15, v14, v13
	v_fma_f32 v16, -v12, v15, v14
	v_fmac_f32_e32 v15, v16, v13
	v_fma_f32 v12, -v12, v15, v14
	v_div_fmas_f32 v12, v12, v13, v15
	v_div_fixup_f32 v11, v12, v11, 1.0
	v_mul_f32_e32 v5, v5, v11
	v_mul_f32_e32 v11, 0xbfb8aa3b, v17
	v_exp_f32_e32 v11, v11
	s_nop 0
	v_add_f32_e32 v11, 1.0, v11
	v_div_scale_f32 v12, s[2:3], v11, v11, 1.0
	v_rcp_f32_e32 v13, v12
	s_nop 0
	v_fma_f32 v14, -v12, v13, 1.0
	v_fmac_f32_e32 v13, v14, v13
	v_div_scale_f32 v14, vcc, 1.0, v11, 1.0
	v_mul_f32_e32 v15, v14, v13
	v_fma_f32 v16, -v12, v15, v14
	v_fmac_f32_e32 v15, v16, v13
	v_fma_f32 v12, -v12, v15, v14
	v_div_fmas_f32 v12, v12, v13, v15
	v_div_fixup_f32 v11, v12, v11, 1.0
	v_mul_f32_e32 v6, v6, v11
	v_div_scale_f32 v11, s[2:3], v2, v2, 1.0
	v_rcp_f32_e32 v12, v11
	s_nop 0
	v_fma_f32 v13, -v11, v12, 1.0
	v_fmac_f32_e32 v12, v13, v12
	v_div_scale_f32 v13, vcc, 1.0, v2, 1.0
	v_mul_f32_e32 v14, v13, v12
	v_fma_f32 v15, -v11, v14, v13
	v_fmac_f32_e32 v14, v15, v12
	v_fma_f32 v11, -v11, v14, v13
	v_div_fmas_f32 v11, v11, v12, v14
	v_div_fixup_f32 v2, v11, v2, 1.0
	v_mul_f32_e32 v7, v7, v2
	v_cvt_pk_bf16_f32 v2, v3, v8
	v_cvt_pk_bf16_f32 v3, v9, v10
	v_cvt_pk_bf16_f32 v4, v4, v5
	v_cvt_pk_bf16_f32 v5, v6, v7
	buffer_store_dwordx4 v[2:5], v1, s[80:83], 0 offen offset:256 sc1
	s_andn2_b64 vcc, exec, s[42:43]
	s_cbranch_vccnz .LBB0_892
